# item-end and mid-item block barriers in mixer items wait only lgkmcnt (store acks drain into the next item; the grid barrier still drains vmcnt)
# baseline (speedup 1.0000x reference)
; __device__ __forceinline__ float siluf(float x) { return x * __builtin_amdgcn_rcpf(1.0f + __expf(-x)); }
; #define BSYNC() do { asm volatile("s_waitcnt vmcnt(0) lgkmcnt(0)" ::: "memory"); __syncthreads(); } while (0)
; template <int TY> __device__ __forceinline__ void mc_item(const Params& p, ldsp lds, int item) {
;     ...
;     BSYNC();
; #pragma unroll
;     for (int tk = 0; tk < 4; ++tk) { float s = 0.f;
; #pragma unroll
;         for (int w = 0; w < 8; ++w) s += RED[w * 64 + 16 * tk + l15];
;         rstd[tk] = rsqrtf(s * (1.0f / DV) + EPS); }
;     const float* nwp = TY == 0 ? p.in[12] : (TY == 1 ? p.in[14] : p.in[17]);
;     const int goff = TY == 0 ? E_RA + h * 128 : (TY == 1 ? E_GB + h * 128 : O_G + h * 512);
;     constexpr int LDY = TY == 2 ? 2048 : 1024; const int ycol = TY == 0 ? h * 128 : (TY == 1 ? 512 + h * 128 : h * 512);
;     bf16_t* Y = (bf16_t*)(p.ws + WS_Y);
; #pragma unroll
;     for (int ei = 0; ei < ET; ++ei) { const int e0 = 16 * (wave * ET + ei) + 4 * q4; const f32x4 w4 = *(const f32x4*)(nwp + e0);
; #pragma unroll
;         for (int tk = 0; tk < 4; ++tk) { const size_t row = (size_t)row0 + 16 * tk + l15;
;             const u32x2 gw = *(const u32x2*)(Pb + row * PP + goff + e0);
;             const float g0 = bf2f(gw.x & 0xffffu), g1 = bf2f(gw.x >> 16), g2 = bf2f(gw.y & 0xffffu), g3 = bf2f(gw.y >> 16);
;             const f32x4 v = acc[ei][tk] * rstd[tk] * w4;
;             float y0 = v[0] * siluf(g0), y1 = v[1] * siluf(g1), y2 = v[2] * siluf(g2), y3 = v[3] * siluf(g3);
.LBB0_877:
	s_or_b64 exec, exec, s[0:1]
	v_or_b32_e32 v72, s9, v151
	s_lshl_b32 s9, s59, 1
	s_add_u32 s0, s26, s9
	s_addc_u32 s1, s27, 0
	v_or_b32_e32 v84, s58, v150
	v_mov_b64_e32 v[90:91], s[0:1]
	s_waitcnt lgkmcnt(0)
	v_mad_i64_i32 v[62:63], s[0:1], v84, s56, v[90:91]
	v_ashrrev_i32_e32 v73, 31, v72
	v_lshl_add_u64 v[74:75], v[62:63], 0, s[48:49]
	v_lshlrev_b64 v[82:83], 1, v[72:73]
	v_lshl_add_u64 v[76:77], v[74:75], 0, v[82:83]
	s_waitcnt vmcnt(0) lgkmcnt(0)
	s_barrier
	global_load_dwordx2 v[186:187], v[76:77], off
	v_lshl_add_u64 v[188:189], v[72:73], 2, s[62:63]
	global_load_dwordx4 v[190:193], v[188:189], off
	v_or_b32_e32 v194, s58, v146
	v_mad_i64_i32 v[196:197], s[0:1], v194, s56, v[90:91]
	v_lshl_add_u64 v[198:199], v[196:197], 0, s[48:49]
	v_lshl_add_u64 v[200:201], v[198:199], 0, v[82:83]
	global_load_dwordx2 v[202:203], v[200:201], off
	v_or_b32_e32 v204, 32, v84
	v_mad_i64_i32 v[206:207], s[0:1], v204, s56, v[90:91]
	v_lshl_add_u64 v[208:209], v[206:207], 0, s[48:49]
	v_lshl_add_u64 v[210:211], v[208:209], 0, v[82:83]
	v_or_b32_e32 v212, 48, v84
	global_load_dwordx2 v[214:215], v[210:211], off
	v_mad_i64_i32 v[216:217], s[0:1], v212, s56, v[90:91]
	v_lshl_add_u64 v[218:219], v[216:217], 0, s[48:49]
	v_lshl_add_u64 v[220:221], v[218:219], 0, v[82:83]
	global_load_dwordx2 v[222:223], v[220:221], off
	v_or_b32_e32 v224, 16, v72
	v_ashrrev_i32_e32 v225, 31, v224
	v_lshlrev_b64 v[226:227], 1, v[224:225]
	v_lshl_add_u64 v[228:229], v[74:75], 0, v[226:227]
	global_load_dwordx2 v[230:231], v[228:229], off
	global_load_dwordx4 v[232:235], v[188:189], off offset:64
	v_lshl_add_u64 v[236:237], v[198:199], 0, v[226:227]
	global_load_dwordx2 v[238:239], v[236:237], off
	v_lshl_add_u64 v[240:241], v[208:209], 0, v[226:227]
	global_load_dwordx2 v[242:243], v[240:241], off
	v_lshl_add_u64 v[244:245], v[218:219], 0, v[226:227]
	global_load_dwordx2 v[246:247], v[244:245], off
	v_or_b32_e32 v248, 32, v72
	v_ashrrev_i32_e32 v249, 31, v248
	v_lshlrev_b64 v[120:121], 1, v[248:249]
	v_lshl_add_u64 v[122:123], v[74:75], 0, v[120:121]
	global_load_dwordx2 v[124:125], v[122:123], off
	v_lshl_add_u64 v[126:127], v[198:199], 0, v[120:121]
	global_load_dwordx4 v[128:131], v[188:189], off offset:128
	global_load_dwordx2 v[132:133], v[126:127], off
	v_lshl_add_u64 v[134:135], v[208:209], 0, v[120:121]
	global_load_dwordx2 v[136:137], v[134:135], off
	v_lshl_add_u64 v[140:141], v[218:219], 0, v[120:121]
	global_load_dwordx2 v[142:143], v[140:141], off
	v_or_b32_e32 v144, 48, v72
	v_ashrrev_i32_e32 v145, 31, v144
	v_lshlrev_b64 v[148:149], 1, v[144:145]
	v_lshl_add_u64 v[152:153], v[74:75], 0, v[148:149]
	global_load_dwordx2 v[154:155], v[152:153], off
	v_lshl_add_u64 v[156:157], v[198:199], 0, v[148:149]
	global_load_dwordx4 v[172:175], v[188:189], off offset:192
	global_load_dwordx2 v[158:159], v[156:157], off
	v_lshl_add_u64 v[162:163], v[208:209], 0, v[148:149]
	global_load_dwordx2 v[166:167], v[162:163], off
	v_lshl_add_u64 v[176:177], v[218:219], 0, v[148:149]
	global_load_dwordx2 v[178:179], v[176:177], off
	v_lshl_add_u64 v[70:71], v[72:73], 2, s[62:63]
	v_lshl_add_u32 v16, v150, 2, 0
	v_add_u32_e32 v16, 0x24c00, v16
	ds_read2_b32 v[76:77], v16 offset1:16
	ds_read2_b32 v[80:81], v16 offset0:64 offset1:80
	ds_read2_b32 v[86:87], v16 offset0:128 offset1:144
	ds_read2_b32 v[108:109], v16 offset0:192 offset1:208
	v_add_u32_e32 v73, 0x400, v16
	s_waitcnt lgkmcnt(3)
	v_mov_b32_e32 v118, v77
	v_mov_b32_e32 v119, v76
	s_waitcnt lgkmcnt(2)
	v_mov_b32_e32 v76, v81
	v_mov_b32_e32 v77, v80
	s_waitcnt lgkmcnt(1)
	v_mov_b32_e32 v80, v87
	v_mov_b32_e32 v81, v86
	s_waitcnt lgkmcnt(0)
	v_mov_b32_e32 v86, v109
	v_mov_b32_e32 v87, v108
	v_pk_add_f32 v[108:109], v[118:119], 0 op_sel_hi:[1,0]
	ds_read2_b32 v[106:107], v16 offset0:32 offset1:48
	ds_read2_b32 v[102:103], v16 offset0:96 offset1:112
	ds_read2_b32 v[98:99], v16 offset0:160 offset1:176
	ds_read2_b32 v[94:95], v16 offset0:224 offset1:240
	ds_read2_b32 v[110:111], v73 offset1:16
	ds_read2_b32 v[112:113], v73 offset0:64 offset1:80
	ds_read2_b32 v[114:115], v73 offset0:128 offset1:144
	ds_read2_b32 v[116:117], v73 offset0:192 offset1:208
	ds_read2_b32 v[104:105], v73 offset0:32 offset1:48
	ds_read2_b32 v[100:101], v73 offset0:96 offset1:112
	ds_read2_b32 v[96:97], v73 offset0:160 offset1:176
	ds_read2_b32 v[92:93], v73 offset0:224 offset1:240
	v_pk_add_f32 v[76:77], v[108:109], v[76:77]
	s_waitcnt lgkmcnt(7)
	v_mov_b32_e32 v118, v111
	v_pk_add_f32 v[76:77], v[76:77], v[80:81]
	v_mov_b32_e32 v119, v110
	v_pk_add_f32 v[76:77], v[76:77], v[86:87]
	s_waitcnt lgkmcnt(6)
	v_mov_b32_e32 v110, v113
	v_mov_b32_e32 v111, v112
	v_pk_add_f32 v[76:77], v[76:77], v[118:119]
	s_waitcnt lgkmcnt(5)
	v_mov_b32_e32 v112, v115
	v_mov_b32_e32 v113, v114
	v_pk_add_f32 v[76:77], v[76:77], v[110:111]
	s_mov_b32 s0, 0x358637bd
	s_waitcnt lgkmcnt(4)
	v_mov_b32_e32 v114, v117
	v_mov_b32_e32 v115, v116
	v_pk_add_f32 v[76:77], v[76:77], v[112:113]
	v_mov_b64_e32 v[88:89], s[0:1]
	v_mov_b32_e32 v85, s8
	v_pk_add_f32 v[76:77], v[76:77], v[114:115]
	s_mov_b32 s8, 0x3b000000
	v_pk_fma_f32 v[76:77], v[76:77], s[8:9], v[88:89] op_sel_hi:[1,0,0]
	s_add_u32 s0, s61, s9
	v_mul_f32_e32 v16, 0x4b800000, v77
	v_cmp_gt_f32_e32 vcc, s33, v77
	v_readlane_b32 s1, v253, 31
	s_addc_u32 s1, s1, 0
	v_cndmask_b32_e32 v16, v77, v16, vcc
	v_rsq_f32_e32 v16, v16
	v_lshl_add_u64 v[86:87], s[0:1], 0, v[82:83]
	s_add_i32 s37, s37, s70
	s_add_i32 s36, s36, s70
	v_mul_f32_e32 v73, 0x45800000, v16
	v_cndmask_b32_e32 v16, v16, v73, vcc
	v_pk_mul_f32 v[66:67], v[66:67], v[16:17] op_sel_hi:[1,0]
	v_pk_mul_f32 v[68:69], v[68:69], v[16:17] op_sel_hi:[1,0]
	v_cmp_gt_f32_e32 vcc, s33, v76
	v_pk_mul_f32 v[46:47], v[46:47], v[16:17] op_sel_hi:[1,0]
	v_pk_mul_f32 v[48:49], v[48:49], v[16:17] op_sel_hi:[1,0]
	v_pk_mul_f32 v[30:31], v[30:31], v[16:17] op_sel_hi:[1,0]
	v_pk_mul_f32 v[32:33], v[32:33], v[16:17] op_sel_hi:[1,0]
	v_pk_mul_f32 v[12:13], v[12:13], v[16:17] op_sel_hi:[1,0]
	v_pk_mul_f32 v[14:15], v[14:15], v[16:17] op_sel_hi:[1,0]
	s_cmpk_lt_i32 s37, 0x400
	s_waitcnt vmcnt(0)
; __device__ __forceinline__ unsigned pk2(float lo, float hi) { return pg8::cvt_pk_bf16(lo, hi); }
; __device__ __forceinline__ float siluf(float x) { return x * __builtin_amdgcn_rcpf(1.0f + __expf(-x)); }
; template <int TY> __device__ __forceinline__ void mc_item(const Params& p, ldsp lds, int item) {
;     ...
;     for (int ei = 0; ei < ET; ++ei) { const int e0 = 16 * (wave * ET + ei) + 4 * q4; const f32x4 w4 = *(const f32x4*)(nwp + e0);
; #pragma unroll
;         for (int tk = 0; tk < 4; ++tk) { const size_t row = (size_t)row0 + 16 * tk + l15;
;             const u32x2 gw = *(const u32x2*)(Pb + row * PP + goff + e0);
;             const float g0 = bf2f(gw.x & 0xffffu), g1 = bf2f(gw.x >> 16), g2 = bf2f(gw.y & 0xffffu), g3 = bf2f(gw.y >> 16);
;             const f32x4 v = acc[ei][tk] * rstd[tk] * w4;
;             float y0 = v[0] * siluf(g0), y1 = v[1] * siluf(g1), y2 = v[2] * siluf(g2), y3 = v[3] * siluf(g3);
;     ...
;             if (!(fabsf(y0) < 1e30f)) y0 = 0.f; if (!(fabsf(y1) < 1e30f)) y1 = 0.f; if (!(fabsf(y2) < 1e30f)) y2 = 0.f; if (!(fabsf(y3) < 1e30f)) y3 = 0.f;
;     ...
;             u32x2 o; o.x = pk2(y0, y1); o.y = pk2(y2, y3);
;             *(u32x2*)(Y + row * LDY + ycol + e0) = o; } }
	v_lshlrev_b32_e32 v73, 16, v186
	v_mul_f32_e32 v80, 0xbfb8aa3b, v73
	v_exp_f32_e32 v80, v80
	v_and_b32_e32 v77, 0xffff0000, v186
	v_lshlrev_b32_e32 v78, 16, v187
	v_and_b32_e32 v79, 0xffff0000, v187
	v_mul_f32_e32 v81, 0xbfb8aa3b, v77
	v_mul_f32_e32 v108, 0xbfb8aa3b, v78
	v_mul_f32_e32 v109, 0xbfb8aa3b, v79
	v_exp_f32_e32 v81, v81
	v_add_f32_e32 v80, 1.0, v80
	v_exp_f32_e32 v108, v108
	v_exp_f32_e32 v109, v109
	v_rcp_f32_e32 v80, v80
	v_add_f32_e32 v81, 1.0, v81
	v_pk_mul_f32 v[66:67], v[66:67], v[190:191]
	v_add_f32_e32 v108, 1.0, v108
	v_rcp_f32_e32 v81, v81
	v_add_f32_e32 v109, 1.0, v109
	v_mul_f32_e32 v73, v80, v73
	v_rcp_f32_e32 v108, v108
	v_mul_f32_e32 v66, v66, v73
	v_rcp_f32_e32 v73, v109
	v_mul_f32_e32 v77, v81, v77
	v_pk_mul_f32 v[68:69], v[68:69], v[192:193]
	v_mul_f32_e32 v67, v67, v77
	v_mul_f32_e32 v77, v108, v78
	v_mul_f32_e32 v73, v73, v79
	v_mul_f32_e32 v68, v68, v77
	v_mul_f32_e32 v69, v69, v73
	v_cvt_pk_bf16_f32 v66, v66, v67
	v_cvt_pk_bf16_f32 v67, v68, v69
	v_lshlrev_b64 v[68:69], 12, v[84:85]
	v_lshl_add_u64 v[78:79], v[86:87], 0, v[68:69]
	global_store_dwordx2 v[78:79], v[66:67], off
	v_or_b32_e32 v66, s58, v146
	v_mad_i64_i32 v[68:69], s[0:1], v66, s56, v[90:91]
	v_lshl_add_u64 v[80:81], v[68:69], 0, s[48:49]
	v_lshl_add_u64 v[68:69], v[80:81], 0, v[82:83]
	v_mul_f32_e32 v73, 0x4b800000, v76
	v_cndmask_b32_e32 v73, v76, v73, vcc
	v_rsq_f32_e32 v73, v73
	v_mov_b32_e32 v67, v85
	v_or_b32_e32 v108, 32, v84
	v_lshlrev_b64 v[66:67], 12, v[66:67]
	v_mul_f32_e32 v76, 0x45800000, v73
	v_cndmask_b32_e32 v76, v73, v76, vcc
	v_pk_mul_f32 v[58:59], v[58:59], v[76:77] op_sel_hi:[1,0]
	v_pk_mul_f32 v[60:61], v[60:61], v[76:77] op_sel_hi:[1,0]
	v_mad_i64_i32 v[68:69], s[0:1], v108, s56, v[90:91]
	v_pk_mul_f32 v[58:59], v[58:59], v[190:191]
	v_lshl_add_u64 v[68:69], v[68:69], 0, s[48:49]
	v_lshl_add_u64 v[66:67], v[86:87], 0, v[66:67]
	v_pk_mul_f32 v[60:61], v[60:61], v[192:193]
	v_lshl_add_u64 v[112:113], v[68:69], 0, v[82:83]
	v_or_b32_e32 v84, 48, v84
	v_lshlrev_b32_e32 v73, 16, v202
	v_and_b32_e32 v77, 0xffff0000, v202
	v_lshlrev_b32_e32 v109, 16, v203
	v_and_b32_e32 v110, 0xffff0000, v203
	v_mul_f32_e32 v111, 0xbfb8aa3b, v73
	v_mul_f32_e32 v114, 0xbfb8aa3b, v77
	v_mul_f32_e32 v115, 0xbfb8aa3b, v109
	v_mul_f32_e32 v116, 0xbfb8aa3b, v110
	v_exp_f32_e32 v111, v111
	v_exp_f32_e32 v114, v114
	v_exp_f32_e32 v115, v115
	v_exp_f32_e32 v116, v116
	v_add_f32_e32 v111, 1.0, v111
	v_add_f32_e32 v114, 1.0, v114
	v_add_f32_e32 v115, 1.0, v115
	v_add_f32_e32 v116, 1.0, v116
	v_rcp_f32_e32 v111, v111
	v_rcp_f32_e32 v114, v114
	v_rcp_f32_e32 v115, v115
	v_rcp_f32_e32 v116, v116
	v_mul_f32_e32 v73, v111, v73
	v_mul_f32_e32 v77, v114, v77
	v_mul_f32_e32 v109, v115, v109
	v_mul_f32_e32 v110, v116, v110
	v_mul_f32_e32 v58, v58, v73
	v_mul_f32_e32 v59, v59, v77
	v_mul_f32_e32 v60, v60, v109
	v_mul_f32_e32 v61, v61, v110
	v_cvt_pk_bf16_f32 v58, v58, v59
	v_cvt_pk_bf16_f32 v59, v60, v61
	global_store_dwordx2 v[66:67], v[58:59], off
	v_mad_i64_i32 v[60:61], s[0:1], v84, s56, v[90:91]
	v_mov_b32_e32 v90, v107
	v_mov_b32_e32 v91, v106
	v_mov_b32_e32 v106, v103
	v_mov_b32_e32 v107, v102
	v_pk_add_f32 v[90:91], v[90:91], 0 op_sel_hi:[1,0]
	v_mov_b32_e32 v102, v99
	v_mov_b32_e32 v103, v98
	v_pk_add_f32 v[90:91], v[90:91], v[106:107]
	v_mov_b32_e32 v98, v95
	v_mov_b32_e32 v99, v94
	v_pk_add_f32 v[90:91], v[90:91], v[102:103]
	s_waitcnt lgkmcnt(3)
	v_mov_b32_e32 v94, v105
	v_mov_b32_e32 v95, v104
	v_pk_add_f32 v[90:91], v[90:91], v[98:99]
	s_waitcnt lgkmcnt(2)
	v_mov_b32_e32 v104, v101
	v_mov_b32_e32 v105, v100
	v_pk_add_f32 v[90:91], v[90:91], v[94:95]
	s_waitcnt lgkmcnt(1)
	v_mov_b32_e32 v100, v97
	v_mov_b32_e32 v101, v96
	v_pk_add_f32 v[90:91], v[90:91], v[104:105]
	s_waitcnt lgkmcnt(0)
	v_mov_b32_e32 v96, v93
	v_mov_b32_e32 v97, v92
	v_pk_add_f32 v[90:91], v[90:91], v[100:101]
	v_lshl_add_u64 v[60:61], v[60:61], 0, s[48:49]
	v_pk_add_f32 v[90:91], v[90:91], v[96:97]
	v_mov_b32_e32 v109, v85
	v_pk_fma_f32 v[88:89], v[90:91], s[8:9], v[88:89] op_sel_hi:[1,0,0]
	v_lshl_add_u64 v[90:91], v[60:61], 0, v[82:83]
	v_mul_f32_e32 v73, 0x4b800000, v89
	v_cmp_gt_f32_e32 vcc, s33, v89
	v_lshlrev_b64 v[58:59], 12, v[108:109]
	v_lshl_add_u64 v[58:59], v[86:87], 0, v[58:59]
	v_cndmask_b32_e32 v73, v89, v73, vcc
	v_rsq_f32_e32 v73, v73
	v_and_b32_e32 v89, 0xffff0000, v215
	v_mul_f32_e32 v77, 0x45800000, v73
	v_cndmask_b32_e32 v82, v73, v77, vcc
	v_lshlrev_b32_e32 v73, 16, v214
	v_and_b32_e32 v77, 0xffff0000, v214
	v_pk_mul_f32 v[54:55], v[54:55], v[82:83] op_sel_hi:[1,0]
	v_pk_mul_f32 v[56:57], v[56:57], v[82:83] op_sel_hi:[1,0]
	v_lshlrev_b32_e32 v83, 16, v215
	v_mul_f32_e32 v92, 0xbfb8aa3b, v73
	v_mul_f32_e32 v93, 0xbfb8aa3b, v77
	v_mul_f32_e32 v94, 0xbfb8aa3b, v83
	v_mul_f32_e32 v95, 0xbfb8aa3b, v89
	v_exp_f32_e32 v92, v92
	v_exp_f32_e32 v93, v93
	v_exp_f32_e32 v94, v94
	v_exp_f32_e32 v95, v95
	v_add_f32_e32 v92, 1.0, v92
	v_add_f32_e32 v93, 1.0, v93
	v_add_f32_e32 v94, 1.0, v94
	v_add_f32_e32 v95, 1.0, v95
	v_rcp_f32_e32 v92, v92
	v_rcp_f32_e32 v93, v93
	v_rcp_f32_e32 v94, v94
	v_rcp_f32_e32 v95, v95
	v_pk_mul_f32 v[54:55], v[190:191], v[54:55]
	v_mul_f32_e32 v73, v92, v73
	v_mul_f32_e32 v77, v93, v77
	v_pk_mul_f32 v[56:57], v[192:193], v[56:57]
	v_mul_f32_e32 v83, v94, v83
	v_mul_f32_e32 v89, v95, v89
	v_mul_f32_e32 v54, v54, v73
	v_mul_f32_e32 v55, v55, v77
	v_mul_f32_e32 v56, v56, v83
	v_mul_f32_e32 v57, v57, v89
	v_cvt_pk_bf16_f32 v54, v54, v55
	v_cvt_pk_bf16_f32 v55, v56, v57
	global_store_dwordx2 v[58:59], v[54:55], off
	v_mul_f32_e32 v57, 0x4b800000, v88
	v_cmp_gt_f32_e32 vcc, s33, v88
	v_or_b32_e32 v56, 16, v72
	s_nop 0
	v_cndmask_b32_e32 v57, v88, v57, vcc
; __device__ __forceinline__ unsigned pk2(float lo, float hi) { return pg8::cvt_pk_bf16(lo, hi); }
; __device__ __forceinline__ float siluf(float x) { return x * __builtin_amdgcn_rcpf(1.0f + __expf(-x)); }
; template <int TY> __device__ __forceinline__ void mc_item(const Params& p, ldsp lds, int item) {
;     ...
;     for (int ei = 0; ei < ET; ++ei) { const int e0 = 16 * (wave * ET + ei) + 4 * q4; const f32x4 w4 = *(const f32x4*)(nwp + e0);
; #pragma unroll
;         for (int tk = 0; tk < 4; ++tk) { const size_t row = (size_t)row0 + 16 * tk + l15;
;             const u32x2 gw = *(const u32x2*)(Pb + row * PP + goff + e0);
;             const float g0 = bf2f(gw.x & 0xffffu), g1 = bf2f(gw.x >> 16), g2 = bf2f(gw.y & 0xffffu), g3 = bf2f(gw.y >> 16);
;             const f32x4 v = acc[ei][tk] * rstd[tk] * w4;
;             float y0 = v[0] * siluf(g0), y1 = v[1] * siluf(g1), y2 = v[2] * siluf(g2), y3 = v[3] * siluf(g3);
;     ...
;             if (!(fabsf(y0) < 1e30f)) y0 = 0.f; if (!(fabsf(y1) < 1e30f)) y1 = 0.f; if (!(fabsf(y2) < 1e30f)) y2 = 0.f; if (!(fabsf(y3) < 1e30f)) y3 = 0.f;
;     ...
;             u32x2 o; o.x = pk2(y0, y1); o.y = pk2(y2, y3);
;             *(u32x2*)(Y + row * LDY + ycol + e0) = o; } }
	v_rsq_f32_e32 v73, v57
	v_ashrrev_i32_e32 v57, 31, v56
	v_lshlrev_b64 v[88:89], 1, v[56:57]
	v_lshl_add_u64 v[90:91], v[74:75], 0, v[88:89]
	v_mul_f32_e32 v56, 0x45800000, v73
	v_cndmask_b32_e32 v56, v73, v56, vcc
	v_pk_mul_f32 v[50:51], v[50:51], v[56:57] op_sel_hi:[1,0]
	v_pk_mul_f32 v[52:53], v[52:53], v[56:57] op_sel_hi:[1,0]
	v_pk_mul_f32 v[50:51], v[190:191], v[50:51]
	v_pk_mul_f32 v[52:53], v[192:193], v[52:53]
	v_lshlrev_b32_e32 v57, 16, v222
	v_and_b32_e32 v54, 0xffff0000, v222
	v_lshlrev_b32_e32 v62, 16, v223
	v_and_b32_e32 v55, 0xffff0000, v223
	v_mul_f32_e32 v63, 0xbfb8aa3b, v57
	v_mul_f32_e32 v64, 0xbfb8aa3b, v54
	v_mul_f32_e32 v65, 0xbfb8aa3b, v62
	v_mul_f32_e32 v73, 0xbfb8aa3b, v55
	v_exp_f32_e32 v63, v63
	v_exp_f32_e32 v64, v64
	v_exp_f32_e32 v65, v65
	v_exp_f32_e32 v73, v73
	v_add_f32_e32 v63, 1.0, v63
	v_add_f32_e32 v64, 1.0, v64
	v_add_f32_e32 v65, 1.0, v65
	v_add_f32_e32 v73, 1.0, v73
	v_rcp_f32_e32 v63, v63
	v_rcp_f32_e32 v64, v64
	v_rcp_f32_e32 v65, v65
	v_rcp_f32_e32 v73, v73
	v_mul_f32_e32 v57, v63, v57
	v_mul_f32_e32 v54, v64, v54
	v_mul_f32_e32 v62, v65, v62
	v_mul_f32_e32 v55, v73, v55
	v_mul_f32_e32 v50, v50, v57
	v_mul_f32_e32 v51, v51, v54
	v_mul_f32_e32 v52, v52, v62
	v_mul_f32_e32 v53, v53, v55
	v_cvt_pk_bf16_f32 v50, v50, v51
	v_cvt_pk_bf16_f32 v51, v52, v53
	v_lshlrev_b64 v[52:53], 12, v[84:85]
	v_lshl_add_u64 v[54:55], v[86:87], 0, v[52:53]
	global_store_dwordx2 v[54:55], v[50:51], off
	v_lshl_add_u64 v[64:65], v[80:81], 0, v[88:89]
	v_lshlrev_b32_e32 v57, 16, v230
	v_and_b32_e32 v62, 0xffff0000, v230
	v_lshlrev_b32_e32 v73, 16, v231
	v_and_b32_e32 v63, 0xffff0000, v231
	v_mul_f32_e32 v77, 0xbfb8aa3b, v57
	v_mul_f32_e32 v83, 0xbfb8aa3b, v62
	v_mul_f32_e32 v84, 0xbfb8aa3b, v73
	v_mul_f32_e32 v85, 0xbfb8aa3b, v63
	v_exp_f32_e32 v77, v77
	v_exp_f32_e32 v83, v83
	v_exp_f32_e32 v84, v84
	v_exp_f32_e32 v85, v85
	v_add_f32_e32 v77, 1.0, v77
	v_add_f32_e32 v83, 1.0, v83
	v_add_f32_e32 v84, 1.0, v84
	v_add_f32_e32 v85, 1.0, v85
	v_rcp_f32_e32 v77, v77
	v_rcp_f32_e32 v83, v83
	v_rcp_f32_e32 v84, v84
	v_rcp_f32_e32 v85, v85
	v_pk_mul_f32 v[46:47], v[46:47], v[232:233]
	v_mul_f32_e32 v57, v77, v57
	v_mul_f32_e32 v62, v83, v62
	v_pk_mul_f32 v[48:49], v[48:49], v[234:235]
	v_mul_f32_e32 v73, v84, v73
	v_mul_f32_e32 v63, v85, v63
	v_mul_f32_e32 v46, v46, v57
	v_mul_f32_e32 v47, v47, v62
	v_mul_f32_e32 v48, v48, v73
	v_mul_f32_e32 v49, v49, v63
	v_cvt_pk_bf16_f32 v46, v46, v47
	v_cvt_pk_bf16_f32 v47, v48, v49
	global_store_dwordx2 v[78:79], v[46:47], off offset:32
	v_pk_mul_f32 v[42:43], v[42:43], v[76:77] op_sel_hi:[1,0]
	v_pk_mul_f32 v[44:45], v[44:45], v[76:77] op_sel_hi:[1,0]
	v_pk_mul_f32 v[42:43], v[42:43], v[232:233]
	v_pk_mul_f32 v[44:45], v[44:45], v[234:235]
	v_lshl_add_u64 v[48:49], v[68:69], 0, v[88:89]
	v_pk_mul_f32 v[38:39], v[38:39], v[82:83] op_sel_hi:[1,0]
	v_pk_mul_f32 v[40:41], v[40:41], v[82:83] op_sel_hi:[1,0]
	v_pk_mul_f32 v[38:39], v[38:39], v[232:233]
	v_pk_mul_f32 v[40:41], v[40:41], v[234:235]
	v_pk_mul_f32 v[26:27], v[26:27], v[76:77] op_sel_hi:[1,0]
	v_pk_mul_f32 v[28:29], v[28:29], v[76:77] op_sel_hi:[1,0]
	v_pk_mul_f32 v[22:23], v[22:23], v[82:83] op_sel_hi:[1,0]
	v_pk_mul_f32 v[24:25], v[24:25], v[82:83] op_sel_hi:[1,0]
	v_pk_mul_f32 v[8:9], v[8:9], v[76:77] op_sel_hi:[1,0]
	v_pk_mul_f32 v[10:11], v[10:11], v[76:77] op_sel_hi:[1,0]
	v_pk_mul_f32 v[4:5], v[4:5], v[82:83] op_sel_hi:[1,0]
	v_pk_mul_f32 v[6:7], v[6:7], v[82:83] op_sel_hi:[1,0]
	v_lshlrev_b32_e32 v57, 16, v238
	v_and_b32_e32 v46, 0xffff0000, v238
	v_lshlrev_b32_e32 v62, 16, v239
	v_and_b32_e32 v47, 0xffff0000, v239
	v_mul_f32_e32 v63, 0xbfb8aa3b, v57
	v_mul_f32_e32 v64, 0xbfb8aa3b, v46
	v_mul_f32_e32 v65, 0xbfb8aa3b, v62
	v_mul_f32_e32 v73, 0xbfb8aa3b, v47
	v_exp_f32_e32 v63, v63
	v_exp_f32_e32 v64, v64
	v_exp_f32_e32 v65, v65
	v_exp_f32_e32 v73, v73
	v_add_f32_e32 v63, 1.0, v63
	v_add_f32_e32 v64, 1.0, v64
	v_add_f32_e32 v65, 1.0, v65
	v_add_f32_e32 v73, 1.0, v73
	v_rcp_f32_e32 v63, v63
	v_rcp_f32_e32 v64, v64
	v_rcp_f32_e32 v65, v65
	v_rcp_f32_e32 v73, v73
	v_mul_f32_e32 v57, v63, v57
	v_mul_f32_e32 v46, v64, v46
	v_mul_f32_e32 v62, v65, v62
	v_mul_f32_e32 v47, v73, v47
	v_mul_f32_e32 v42, v42, v57
	v_mul_f32_e32 v43, v43, v46
	v_mul_f32_e32 v44, v44, v62
	v_mul_f32_e32 v45, v45, v47
	v_cvt_pk_bf16_f32 v42, v42, v43
	v_cvt_pk_bf16_f32 v43, v44, v45
	global_store_dwordx2 v[66:67], v[42:43], off offset:32
	v_lshl_add_u64 v[44:45], v[60:61], 0, v[88:89]
	v_lshlrev_b32_e32 v46, 16, v242
	v_and_b32_e32 v42, 0xffff0000, v242
	v_lshlrev_b32_e32 v47, 16, v243
	v_and_b32_e32 v43, 0xffff0000, v243
	v_mul_f32_e32 v48, 0xbfb8aa3b, v46
	v_mul_f32_e32 v49, 0xbfb8aa3b, v42
	v_mul_f32_e32 v57, 0xbfb8aa3b, v47
	v_mul_f32_e32 v62, 0xbfb8aa3b, v43
	v_exp_f32_e32 v48, v48
	v_exp_f32_e32 v49, v49
	v_exp_f32_e32 v57, v57
	v_exp_f32_e32 v62, v62
	v_add_f32_e32 v48, 1.0, v48
	v_add_f32_e32 v49, 1.0, v49
	v_add_f32_e32 v57, 1.0, v57
	v_add_f32_e32 v62, 1.0, v62
	v_rcp_f32_e32 v48, v48
	v_rcp_f32_e32 v49, v49
	v_rcp_f32_e32 v57, v57
	v_rcp_f32_e32 v62, v62
	v_mul_f32_e32 v46, v48, v46
	v_mul_f32_e32 v42, v49, v42
	v_mul_f32_e32 v47, v57, v47
	v_mul_f32_e32 v43, v62, v43
	v_mul_f32_e32 v38, v38, v46
	v_mul_f32_e32 v39, v39, v42
	v_mul_f32_e32 v40, v40, v47
	v_mul_f32_e32 v41, v41, v43
	v_cvt_pk_bf16_f32 v38, v38, v39
	v_cvt_pk_bf16_f32 v39, v40, v41
	global_store_dwordx2 v[58:59], v[38:39], off offset:32
	v_or_b32_e32 v38, 32, v72
	v_ashrrev_i32_e32 v39, 31, v38
	v_pk_mul_f32 v[34:35], v[34:35], v[56:57] op_sel_hi:[1,0]
	v_lshlrev_b64 v[38:39], 1, v[38:39]
	v_pk_mul_f32 v[36:37], v[36:37], v[56:57] op_sel_hi:[1,0]
	v_pk_mul_f32 v[34:35], v[34:35], v[232:233]
; __device__ __forceinline__ unsigned pk2(float lo, float hi) { return pg8::cvt_pk_bf16(lo, hi); }
; __device__ __forceinline__ float siluf(float x) { return x * __builtin_amdgcn_rcpf(1.0f + __expf(-x)); }
; template <int TY> __device__ __forceinline__ void mc_item(const Params& p, ldsp lds, int item) {
;     ...
;     for (int ei = 0; ei < ET; ++ei) { const int e0 = 16 * (wave * ET + ei) + 4 * q4; const f32x4 w4 = *(const f32x4*)(nwp + e0);
; #pragma unroll
;         for (int tk = 0; tk < 4; ++tk) { const size_t row = (size_t)row0 + 16 * tk + l15;
;             const u32x2 gw = *(const u32x2*)(Pb + row * PP + goff + e0);
;             const float g0 = bf2f(gw.x & 0xffffu), g1 = bf2f(gw.x >> 16), g2 = bf2f(gw.y & 0xffffu), g3 = bf2f(gw.y >> 16);
;             const f32x4 v = acc[ei][tk] * rstd[tk] * w4;
;             float y0 = v[0] * siluf(g0), y1 = v[1] * siluf(g1), y2 = v[2] * siluf(g2), y3 = v[3] * siluf(g3);
;     ...
;             if (!(fabsf(y0) < 1e30f)) y0 = 0.f; if (!(fabsf(y1) < 1e30f)) y1 = 0.f; if (!(fabsf(y2) < 1e30f)) y2 = 0.f; if (!(fabsf(y3) < 1e30f)) y3 = 0.f;
;     ...
;             u32x2 o; o.x = pk2(y0, y1); o.y = pk2(y2, y3);
;             *(u32x2*)(Y + row * LDY + ycol + e0) = o; } }
	v_lshl_add_u64 v[42:43], v[74:75], 0, v[38:39]
	v_pk_mul_f32 v[36:37], v[36:37], v[234:235]
	v_pk_mul_f32 v[18:19], v[18:19], v[56:57] op_sel_hi:[1,0]
	v_pk_mul_f32 v[20:21], v[20:21], v[56:57] op_sel_hi:[1,0]
	v_pk_mul_f32 v[0:1], v[0:1], v[56:57] op_sel_hi:[1,0]
	v_pk_mul_f32 v[2:3], v[2:3], v[56:57] op_sel_hi:[1,0]
	v_lshlrev_b32_e32 v44, 16, v246
	v_and_b32_e32 v40, 0xffff0000, v246
	v_lshlrev_b32_e32 v45, 16, v247
	v_and_b32_e32 v41, 0xffff0000, v247
	v_mul_f32_e32 v46, 0xbfb8aa3b, v44
	v_mul_f32_e32 v47, 0xbfb8aa3b, v40
	v_mul_f32_e32 v48, 0xbfb8aa3b, v45
	v_mul_f32_e32 v49, 0xbfb8aa3b, v41
	v_exp_f32_e32 v46, v46
	v_exp_f32_e32 v47, v47
	v_exp_f32_e32 v48, v48
	v_exp_f32_e32 v49, v49
	v_add_f32_e32 v46, 1.0, v46
	v_add_f32_e32 v47, 1.0, v47
	v_add_f32_e32 v48, 1.0, v48
	v_add_f32_e32 v49, 1.0, v49
	v_rcp_f32_e32 v46, v46
	v_rcp_f32_e32 v47, v47
	v_rcp_f32_e32 v48, v48
	v_rcp_f32_e32 v49, v49
	v_mul_f32_e32 v44, v46, v44
	v_mul_f32_e32 v40, v47, v40
	v_mul_f32_e32 v45, v48, v45
	v_mul_f32_e32 v41, v49, v41
	v_mul_f32_e32 v34, v34, v44
	v_mul_f32_e32 v35, v35, v40
	v_mul_f32_e32 v36, v36, v45
	v_mul_f32_e32 v37, v37, v41
	v_cvt_pk_bf16_f32 v34, v34, v35
	v_cvt_pk_bf16_f32 v35, v36, v37
	v_lshl_add_u64 v[42:43], v[80:81], 0, v[38:39]
	global_store_dwordx2 v[54:55], v[34:35], off offset:32
	v_lshlrev_b32_e32 v44, 16, v124
	v_and_b32_e32 v40, 0xffff0000, v124
	v_lshlrev_b32_e32 v45, 16, v125
	v_and_b32_e32 v41, 0xffff0000, v125
	v_mul_f32_e32 v46, 0xbfb8aa3b, v44
	v_mul_f32_e32 v47, 0xbfb8aa3b, v40
	v_mul_f32_e32 v48, 0xbfb8aa3b, v45
	v_mul_f32_e32 v49, 0xbfb8aa3b, v41
	v_exp_f32_e32 v46, v46
	v_exp_f32_e32 v47, v47
	v_exp_f32_e32 v48, v48
	v_exp_f32_e32 v49, v49
	v_add_f32_e32 v46, 1.0, v46
	v_add_f32_e32 v47, 1.0, v47
	v_add_f32_e32 v48, 1.0, v48
	v_add_f32_e32 v49, 1.0, v49
	v_rcp_f32_e32 v46, v46
	v_rcp_f32_e32 v47, v47
	v_rcp_f32_e32 v48, v48
	v_rcp_f32_e32 v49, v49
	v_pk_mul_f32 v[30:31], v[30:31], v[128:129]
	v_mul_f32_e32 v44, v46, v44
	v_mul_f32_e32 v40, v47, v40
	v_pk_mul_f32 v[32:33], v[32:33], v[130:131]
	v_mul_f32_e32 v45, v48, v45
	v_mul_f32_e32 v41, v49, v41
	v_mul_f32_e32 v30, v30, v44
	v_mul_f32_e32 v31, v31, v40
	v_mul_f32_e32 v32, v32, v45
	v_mul_f32_e32 v33, v33, v41
	v_cvt_pk_bf16_f32 v30, v30, v31
	v_cvt_pk_bf16_f32 v31, v32, v33
	global_store_dwordx2 v[78:79], v[30:31], off offset:64
	v_pk_mul_f32 v[26:27], v[26:27], v[128:129]
	v_pk_mul_f32 v[28:29], v[28:29], v[130:131]
	v_lshl_add_u64 v[32:33], v[68:69], 0, v[38:39]
	v_pk_mul_f32 v[22:23], v[22:23], v[128:129]
	v_pk_mul_f32 v[24:25], v[24:25], v[130:131]
	v_pk_mul_f32 v[18:19], v[18:19], v[128:129]
	v_pk_mul_f32 v[20:21], v[20:21], v[130:131]
	v_lshlrev_b32_e32 v40, 16, v132
	v_and_b32_e32 v30, 0xffff0000, v132
	v_lshlrev_b32_e32 v41, 16, v133
	v_and_b32_e32 v31, 0xffff0000, v133
	v_mul_f32_e32 v42, 0xbfb8aa3b, v40
	v_mul_f32_e32 v43, 0xbfb8aa3b, v30
	v_mul_f32_e32 v44, 0xbfb8aa3b, v41
	v_mul_f32_e32 v45, 0xbfb8aa3b, v31
	v_exp_f32_e32 v42, v42
	v_exp_f32_e32 v43, v43
	v_exp_f32_e32 v44, v44
	v_exp_f32_e32 v45, v45
	v_add_f32_e32 v42, 1.0, v42
	v_add_f32_e32 v43, 1.0, v43
	v_add_f32_e32 v44, 1.0, v44
	v_add_f32_e32 v45, 1.0, v45
	v_rcp_f32_e32 v42, v42
	v_rcp_f32_e32 v43, v43
	v_rcp_f32_e32 v44, v44
	v_rcp_f32_e32 v45, v45
	v_mul_f32_e32 v40, v42, v40
	v_mul_f32_e32 v30, v43, v30
	v_mul_f32_e32 v41, v44, v41
	v_mul_f32_e32 v31, v45, v31
	v_mul_f32_e32 v26, v26, v40
	v_mul_f32_e32 v27, v27, v30
	v_mul_f32_e32 v28, v28, v41
	v_mul_f32_e32 v29, v29, v31
	v_cvt_pk_bf16_f32 v26, v26, v27
	v_cvt_pk_bf16_f32 v27, v28, v29
	global_store_dwordx2 v[66:67], v[26:27], off offset:64
	v_lshl_add_u64 v[28:29], v[60:61], 0, v[38:39]
	v_lshlrev_b32_e32 v30, 16, v136
	v_and_b32_e32 v26, 0xffff0000, v136
	v_lshlrev_b32_e32 v31, 16, v137
	v_and_b32_e32 v27, 0xffff0000, v137
	v_mul_f32_e32 v32, 0xbfb8aa3b, v30
	v_mul_f32_e32 v33, 0xbfb8aa3b, v26
	v_mul_f32_e32 v38, 0xbfb8aa3b, v31
	v_mul_f32_e32 v39, 0xbfb8aa3b, v27
	v_exp_f32_e32 v32, v32
	v_exp_f32_e32 v33, v33
	v_exp_f32_e32 v38, v38
	v_exp_f32_e32 v39, v39
	v_add_f32_e32 v32, 1.0, v32
	v_add_f32_e32 v33, 1.0, v33
	v_add_f32_e32 v38, 1.0, v38
	v_add_f32_e32 v39, 1.0, v39
	v_rcp_f32_e32 v32, v32
	v_rcp_f32_e32 v33, v33
	v_rcp_f32_e32 v38, v38
	v_rcp_f32_e32 v39, v39
	v_mul_f32_e32 v30, v32, v30
	v_mul_f32_e32 v26, v33, v26
	v_mul_f32_e32 v31, v38, v31
	v_mul_f32_e32 v27, v39, v27
	v_mul_f32_e32 v22, v22, v30
	v_mul_f32_e32 v23, v23, v26
	v_mul_f32_e32 v24, v24, v31
	v_mul_f32_e32 v25, v25, v27
	v_cvt_pk_bf16_f32 v22, v22, v23
	v_cvt_pk_bf16_f32 v23, v24, v25
	global_store_dwordx2 v[58:59], v[22:23], off offset:64
	v_or_b32_e32 v22, 48, v72
	v_ashrrev_i32_e32 v23, 31, v22
	v_lshlrev_b64 v[22:23], 1, v[22:23]
	v_lshl_add_u64 v[26:27], v[74:75], 0, v[22:23]
	v_lshlrev_b32_e32 v28, 16, v142
	v_and_b32_e32 v24, 0xffff0000, v142
	v_lshlrev_b32_e32 v29, 16, v143
	v_and_b32_e32 v25, 0xffff0000, v143
	v_mul_f32_e32 v30, 0xbfb8aa3b, v28
	v_mul_f32_e32 v31, 0xbfb8aa3b, v24
	v_mul_f32_e32 v32, 0xbfb8aa3b, v29
	v_mul_f32_e32 v33, 0xbfb8aa3b, v25
	v_exp_f32_e32 v30, v30
	v_exp_f32_e32 v31, v31
	v_exp_f32_e32 v32, v32
	v_exp_f32_e32 v33, v33
; __device__ __forceinline__ unsigned pk2(float lo, float hi) { return pg8::cvt_pk_bf16(lo, hi); }
; __device__ __forceinline__ float siluf(float x) { return x * __builtin_amdgcn_rcpf(1.0f + __expf(-x)); }
; #define BSYNC() do { asm volatile("s_waitcnt vmcnt(0) lgkmcnt(0)" ::: "memory"); __syncthreads(); } while (0)
; template <int TY> __device__ __forceinline__ void mc_item(const Params& p, ldsp lds, int item) {
;     ...
;     for (int ei = 0; ei < ET; ++ei) { const int e0 = 16 * (wave * ET + ei) + 4 * q4; const f32x4 w4 = *(const f32x4*)(nwp + e0);
; #pragma unroll
;         for (int tk = 0; tk < 4; ++tk) { const size_t row = (size_t)row0 + 16 * tk + l15;
;             const u32x2 gw = *(const u32x2*)(Pb + row * PP + goff + e0);
;             const float g0 = bf2f(gw.x & 0xffffu), g1 = bf2f(gw.x >> 16), g2 = bf2f(gw.y & 0xffffu), g3 = bf2f(gw.y >> 16);
;             const f32x4 v = acc[ei][tk] * rstd[tk] * w4;
;             float y0 = v[0] * siluf(g0), y1 = v[1] * siluf(g1), y2 = v[2] * siluf(g2), y3 = v[3] * siluf(g3);
;     ...
;             if (!(fabsf(y0) < 1e30f)) y0 = 0.f; if (!(fabsf(y1) < 1e30f)) y1 = 0.f; if (!(fabsf(y2) < 1e30f)) y2 = 0.f; if (!(fabsf(y3) < 1e30f)) y3 = 0.f;
;     ...
;             u32x2 o; o.x = pk2(y0, y1); o.y = pk2(y2, y3);
;             *(u32x2*)(Y + row * LDY + ycol + e0) = o; } }
;     BSYNC();
	v_add_f32_e32 v30, 1.0, v30
	v_add_f32_e32 v31, 1.0, v31
	v_add_f32_e32 v32, 1.0, v32
	v_add_f32_e32 v33, 1.0, v33
	v_rcp_f32_e32 v30, v30
	v_rcp_f32_e32 v31, v31
	v_rcp_f32_e32 v32, v32
	v_rcp_f32_e32 v33, v33
	v_mul_f32_e32 v28, v30, v28
	v_mul_f32_e32 v24, v31, v24
	v_mul_f32_e32 v29, v32, v29
	v_mul_f32_e32 v25, v33, v25
	v_mul_f32_e32 v18, v18, v28
	v_mul_f32_e32 v19, v19, v24
	v_mul_f32_e32 v20, v20, v29
	v_mul_f32_e32 v21, v21, v25
	v_cvt_pk_bf16_f32 v18, v18, v19
	v_cvt_pk_bf16_f32 v19, v20, v21
	v_lshl_add_u64 v[26:27], v[80:81], 0, v[22:23]
	global_store_dwordx2 v[54:55], v[18:19], off offset:64
	v_lshlrev_b32_e32 v16, 16, v154
	v_and_b32_e32 v24, 0xffff0000, v154
	v_lshlrev_b32_e32 v28, 16, v155
	v_and_b32_e32 v25, 0xffff0000, v155
	v_mul_f32_e32 v29, 0xbfb8aa3b, v16
	v_mul_f32_e32 v30, 0xbfb8aa3b, v24
	v_mul_f32_e32 v31, 0xbfb8aa3b, v28
	v_mul_f32_e32 v32, 0xbfb8aa3b, v25
	v_exp_f32_e32 v29, v29
	v_exp_f32_e32 v30, v30
	v_exp_f32_e32 v31, v31
	v_exp_f32_e32 v32, v32
	v_add_f32_e32 v29, 1.0, v29
	v_add_f32_e32 v30, 1.0, v30
	v_add_f32_e32 v31, 1.0, v31
	v_add_f32_e32 v32, 1.0, v32
	v_rcp_f32_e32 v29, v29
	v_rcp_f32_e32 v30, v30
	v_rcp_f32_e32 v31, v31
	v_rcp_f32_e32 v32, v32
	v_pk_mul_f32 v[12:13], v[12:13], v[172:173]
	v_mul_f32_e32 v16, v29, v16
	v_mul_f32_e32 v24, v30, v24
	v_pk_mul_f32 v[14:15], v[14:15], v[174:175]
	v_mul_f32_e32 v28, v31, v28
	v_mul_f32_e32 v25, v32, v25
	v_mul_f32_e32 v12, v12, v16
	v_mul_f32_e32 v13, v13, v24
	v_mul_f32_e32 v14, v14, v28
	v_mul_f32_e32 v15, v15, v25
	v_cvt_pk_bf16_f32 v12, v12, v13
	v_cvt_pk_bf16_f32 v13, v14, v15
	global_store_dwordx2 v[78:79], v[12:13], off offset:96
	v_pk_mul_f32 v[8:9], v[8:9], v[172:173]
	v_pk_mul_f32 v[10:11], v[10:11], v[174:175]
	v_lshl_add_u64 v[14:15], v[68:69], 0, v[22:23]
	v_pk_mul_f32 v[4:5], v[4:5], v[172:173]
	v_pk_mul_f32 v[6:7], v[6:7], v[174:175]
	v_pk_mul_f32 v[0:1], v[0:1], v[172:173]
	v_pk_mul_f32 v[2:3], v[2:3], v[174:175]
	v_lshlrev_b32_e32 v16, 16, v158
	v_and_b32_e32 v12, 0xffff0000, v158
	v_lshlrev_b32_e32 v24, 16, v159
	v_and_b32_e32 v13, 0xffff0000, v159
	v_mul_f32_e32 v25, 0xbfb8aa3b, v16
	v_mul_f32_e32 v26, 0xbfb8aa3b, v12
	v_mul_f32_e32 v27, 0xbfb8aa3b, v24
	v_mul_f32_e32 v28, 0xbfb8aa3b, v13
	v_exp_f32_e32 v25, v25
	v_exp_f32_e32 v26, v26
	v_exp_f32_e32 v27, v27
	v_exp_f32_e32 v28, v28
	v_add_f32_e32 v25, 1.0, v25
	v_add_f32_e32 v26, 1.0, v26
	v_add_f32_e32 v27, 1.0, v27
	v_add_f32_e32 v28, 1.0, v28
	v_rcp_f32_e32 v25, v25
	v_rcp_f32_e32 v26, v26
	v_rcp_f32_e32 v27, v27
	v_rcp_f32_e32 v28, v28
	v_mul_f32_e32 v16, v25, v16
	v_mul_f32_e32 v12, v26, v12
	v_mul_f32_e32 v24, v27, v24
	v_mul_f32_e32 v13, v28, v13
	v_mul_f32_e32 v8, v8, v16
	v_mul_f32_e32 v9, v9, v12
	v_mul_f32_e32 v10, v10, v24
	v_mul_f32_e32 v11, v11, v13
	v_cvt_pk_bf16_f32 v8, v8, v9
	v_cvt_pk_bf16_f32 v9, v10, v11
	global_store_dwordx2 v[66:67], v[8:9], off offset:96
	v_lshl_add_u64 v[10:11], v[60:61], 0, v[22:23]
	v_lshlrev_b32_e32 v12, 16, v166
	v_and_b32_e32 v8, 0xffff0000, v166
	v_lshlrev_b32_e32 v13, 16, v167
	v_and_b32_e32 v9, 0xffff0000, v167
	v_mul_f32_e32 v14, 0xbfb8aa3b, v12
	v_mul_f32_e32 v15, 0xbfb8aa3b, v8
	v_mul_f32_e32 v16, 0xbfb8aa3b, v13
	v_mul_f32_e32 v22, 0xbfb8aa3b, v9
	v_exp_f32_e32 v14, v14
	v_exp_f32_e32 v15, v15
	v_exp_f32_e32 v16, v16
	v_exp_f32_e32 v22, v22
	v_add_f32_e32 v14, 1.0, v14
	v_add_f32_e32 v15, 1.0, v15
	v_add_f32_e32 v16, 1.0, v16
	v_add_f32_e32 v22, 1.0, v22
	v_rcp_f32_e32 v14, v14
	v_rcp_f32_e32 v15, v15
	v_rcp_f32_e32 v16, v16
	v_rcp_f32_e32 v22, v22
	v_mul_f32_e32 v12, v14, v12
	v_mul_f32_e32 v8, v15, v8
	v_mul_f32_e32 v13, v16, v13
	v_mul_f32_e32 v9, v22, v9
	v_mul_f32_e32 v4, v4, v12
	v_mul_f32_e32 v5, v5, v8
	v_mul_f32_e32 v6, v6, v13
	v_mul_f32_e32 v7, v7, v9
	v_cvt_pk_bf16_f32 v4, v4, v5
	v_cvt_pk_bf16_f32 v5, v6, v7
	global_store_dwordx2 v[58:59], v[4:5], off offset:96
	v_lshlrev_b32_e32 v6, 16, v178
	v_and_b32_e32 v4, 0xffff0000, v178
	v_lshlrev_b32_e32 v7, 16, v179
	v_and_b32_e32 v5, 0xffff0000, v179
	v_mul_f32_e32 v8, 0xbfb8aa3b, v6
	v_mul_f32_e32 v9, 0xbfb8aa3b, v4
	v_mul_f32_e32 v10, 0xbfb8aa3b, v7
	v_mul_f32_e32 v11, 0xbfb8aa3b, v5
	v_exp_f32_e32 v8, v8
	v_exp_f32_e32 v9, v9
	v_exp_f32_e32 v10, v10
	v_exp_f32_e32 v11, v11
	v_add_f32_e32 v8, 1.0, v8
	v_add_f32_e32 v9, 1.0, v9
	v_add_f32_e32 v10, 1.0, v10
	v_add_f32_e32 v11, 1.0, v11
	v_rcp_f32_e32 v8, v8
	v_rcp_f32_e32 v9, v9
	v_rcp_f32_e32 v10, v10
	v_rcp_f32_e32 v11, v11
	v_mul_f32_e32 v6, v8, v6
	v_mul_f32_e32 v4, v9, v4
	v_mul_f32_e32 v7, v10, v7
	v_mul_f32_e32 v5, v11, v5
	v_mul_f32_e32 v0, v0, v6
	v_mul_f32_e32 v1, v1, v4
	v_mul_f32_e32 v2, v2, v7
	v_mul_f32_e32 v3, v3, v5
	v_cvt_pk_bf16_f32 v0, v0, v1
	v_cvt_pk_bf16_f32 v1, v2, v3
	global_store_dwordx2 v[54:55], v[0:1], off offset:96
	v_mov_b32_e32 v18, v172
	v_mov_b32_e32 v19, v173
	v_mov_b32_e32 v20, v174
	v_mov_b32_e32 v21, v175
	v_mov_b32_e32 v34, v128
	v_mov_b32_e32 v35, v129
	v_mov_b32_e32 v36, v130
	v_mov_b32_e32 v37, v131
	v_mov_b32_e32 v50, v232
	v_mov_b32_e32 v51, v233
	v_mov_b32_e32 v52, v234
	v_mov_b32_e32 v53, v235
	v_mov_b32_e32 v110, v214
	v_mov_b32_e32 v111, v215
	s_waitcnt lgkmcnt(0)
	s_barrier
	s_cbranch_scc0 .LBB0_853

; __device__ __forceinline__ unsigned f2bf(float f) { unsigned u = __builtin_bit_cast(unsigned, f); return (u + 0x7fffu + ((u >> 16) & 1u)) >> 16; }
; __device__ __forceinline__ float siluf(float x) { return x * __builtin_amdgcn_rcpf(1.0f + __expf(-x)); }
; #define BSYNC() do { asm volatile("s_waitcnt vmcnt(0) lgkmcnt(0)" ::: "memory"); __syncthreads(); } while (0)
; template <int TY> __device__ __forceinline__ void sample_item(const Params& p, ldsp lds, int item) {
;     ...
;     { const int t = wave; float val[DV / 64]; float ssq = 0.f;
; #pragma unroll
;       for (int i = 0; i < DV / 64; ++i) { const int e = lane + 64 * i; float a = 0.f;
;           for (int g = 0; g < NG; ++g) a += OP[(g * 8 + t) * DV + e];
;           for (int s = 0; s <= t; ++s) a += As[t * 8 + s] * Vs[s * DV + e];
;           val[i] = a; ssq += a * a; }
;       ssq = wave_sum(ssq); const float rstd = rsqrtf(ssq * (1.0f / DV) + EPS);
;       const float* nwp = TY == 0 ? p.in[12] : (TY == 1 ? p.in[14] : p.in[17]);
;       const int goff = TY == 0 ? E_RA + h * 128 : (TY == 1 ? E_GB + h * 128 : O_G + h * 512);
;       constexpr int LDY = TY == 2 ? 2048 : 1024; const int ycol = TY == 0 ? h * 128 : (TY == 1 ? 512 + h * 128 : h * 512);
;       bf16_t* Y = (bf16_t*)(p.ws + WS_Y) + (size_t)(r0 + t) * LDY + ycol;
; #pragma unroll
;       for (int i = 0; i < DV / 64; ++i) { const int e = lane + 64 * i; const float g = bf2f(Pb[(size_t)t * PP + goff + e]);
;           Y[e] = (bf16_t)f2bf(val[i] * rstd * nwp[e] * siluf(g)); } }
;     BSYNC();
.LBB0_979:
	v_pk_mul_f32 v[2:3], v[0:1], v[0:1]
	s_add_i32 s0, s21, s36
	v_add_f32_e32 v2, v2, v3
	v_xor_b32_e32 v3, 1, v164
	v_cmp_lt_i32_e32 vcc, v3, v165
	s_ashr_i32 s1, s0, 31
	s_lshl_b64 s[0:1], s[0:1], 11
	v_cndmask_b32_e32 v3, v164, v3, vcc
	v_lshlrev_b32_e32 v3, 2, v3
	ds_bpermute_b32 v3, v3, v2
	s_add_u32 s0, s61, s0
	v_readlane_b32 s8, v253, 31
	s_addc_u32 s1, s8, s1
	s_lshl_b32 s8, s37, 1
	s_waitcnt lgkmcnt(0)
	v_add_f32_e32 v2, v2, v3
	v_xor_b32_e32 v3, 2, v164
	v_cmp_lt_i32_e32 vcc, v3, v165
	s_add_u32 s0, s0, s8
	s_addc_u32 s1, s1, 0
	v_cndmask_b32_e32 v3, v164, v3, vcc
	v_lshlrev_b32_e32 v3, 2, v3
	ds_bpermute_b32 v3, v3, v2
	v_cmp_lt_i32_e32 vcc, v184, v165
	s_mul_hi_i32 s9, s21, 0x1e00
	s_mulk_i32 s21, 0x1e00
	s_add_u32 s10, s16, s21
	s_waitcnt lgkmcnt(0)
	v_add_f32_e32 v2, v2, v3
	v_cndmask_b32_e32 v3, v164, v184, vcc
	v_lshlrev_b32_e32 v3, 2, v3
	ds_bpermute_b32 v3, v3, v2
	s_addc_u32 s9, s17, s9
	v_readlane_b32 s76, v252, 20
	s_add_u32 s8, s10, s8
	v_readlane_b32 s77, v252, 21
	s_waitcnt lgkmcnt(0)
	v_add_f32_e32 v2, v2, v3
	v_xor_b32_e32 v3, 8, v164
	v_cmp_lt_i32_e32 vcc, v3, v165
	v_readlane_b32 s78, v252, 22
	v_readlane_b32 s79, v252, 23
	v_cndmask_b32_e32 v3, v164, v3, vcc
	v_lshlrev_b32_e32 v3, 2, v3
	ds_bpermute_b32 v3, v3, v2
	v_cmp_lt_i32_e32 vcc, v170, v165
	v_readlane_b32 s80, v252, 24
	v_readlane_b32 s81, v252, 25
	v_readlane_b32 s82, v252, 26
	s_waitcnt lgkmcnt(0)
	v_add_f32_e32 v2, v2, v3
	v_cndmask_b32_e32 v3, v164, v170, vcc
	v_lshlrev_b32_e32 v3, 2, v3
	ds_bpermute_b32 v3, v3, v2
	v_cmp_lt_i32_e32 vcc, v171, v165
	v_readlane_b32 s83, v252, 27
	v_readlane_b32 s84, v252, 28
	v_readlane_b32 s85, v252, 29
	s_waitcnt lgkmcnt(0)
	v_add_f32_e32 v2, v2, v3
	v_cndmask_b32_e32 v3, v164, v171, vcc
	v_lshlrev_b32_e32 v3, 2, v3
	ds_bpermute_b32 v3, v3, v2
	s_addc_u32 s9, s9, 0
	v_readlane_b32 s86, v252, 30
	v_readlane_b32 s87, v252, 31
	v_readlane_b32 s88, v252, 32
	s_waitcnt lgkmcnt(0)
	v_add_f32_e32 v2, v2, v3
	v_mov_b32_e32 v3, 0x358637bd
	v_fmamk_f32 v2, v2, 0x3c000000, v3
	v_cmp_gt_f32_e32 vcc, s33, v2
	v_mul_f32_e32 v3, 0x4b800000, v2
	v_readlane_b32 s89, v252, 33
	v_cndmask_b32_e32 v2, v2, v3, vcc
	v_rsq_f32_e32 v2, v2
	s_mov_b64 s[76:77], s[80:81]
	v_lshlrev_b32_e32 v5, 2, v116
	s_mov_b64 s[78:79], s[82:83]
	v_mul_f32_e32 v3, 0x45800000, v2
	v_cndmask_b32_e32 v2, v2, v3, vcc
	v_lshlrev_b32_e32 v3, 1, v116
	global_load_ushort v4, v3, s[8:9] offset:2048
	s_mov_b64 s[80:81], s[84:85]
	global_load_dword v6, v5, s[80:81]
	v_mul_f32_e32 v0, v0, v2
	v_mul_f32_e32 v1, v1, v2
	global_load_dword v2, v5, s[80:81] offset:256
	v_readlane_b32 s90, v252, 34
	v_readlane_b32 s91, v252, 35
	s_mov_b64 s[82:83], s[86:87]
	s_mov_b64 s[84:85], s[88:89]
	s_waitcnt vmcnt(0)
	v_lshlrev_b32_e32 v4, 16, v4
	v_mul_f32_e32 v0, v6, v0
	v_mul_f32_e32 v6, 0xbfb8aa3b, v4
	v_exp_f32_e32 v6, v6
	v_mul_f32_e32 v1, v2, v1
	v_add_f32_e32 v6, 1.0, v6
	v_rcp_f32_e32 v6, v6
	s_nop 0
	v_mul_f32_e32 v4, v6, v4
	v_mul_f32_e32 v0, v4, v0
	v_bfe_u32 v4, v0, 16, 1
	v_add3_u32 v0, v0, v4, s52
	global_store_short_d16_hi v3, v0, s[0:1]
	global_load_ushort v0, v3, s[8:9] offset:2176
	s_waitcnt vmcnt(0)
	v_lshlrev_b32_e32 v0, 16, v0
	v_mul_f32_e32 v2, 0xbfb8aa3b, v0
	v_exp_f32_e32 v2, v2
	s_nop 0
	v_add_f32_e32 v2, 1.0, v2
	v_rcp_f32_e32 v2, v2
	s_nop 0
	v_mul_f32_e32 v0, v2, v0
	v_mul_f32_e32 v0, v1, v0
	v_bfe_u32 v1, v0, 16, 1
	v_add3_u32 v0, v0, v1, s52
	global_store_short_d16_hi v3, v0, s[0:1] offset:128
	s_waitcnt lgkmcnt(0)
	s_barrier

; #define LAS __attribute__((address_space(3)))
; #define BSYNC() do { asm volatile("s_waitcnt vmcnt(0) lgkmcnt(0)" ::: "memory"); __syncthreads(); } while (0)
; template <int TY> __device__ __forceinline__ void sample_item(const Params& p, ldsp lds, int item) {
;     ...
;     for (int t = 0; t < 8; ++t) *(LAS f32x4*)(OP + (dg * 8 + t) * DV + e4 * 4) = o[t];
;     BSYNC();
;     { const int t = wave; float val[DV / 64]; float ssq = 0.f;
; #pragma unroll
;       for (int i = 0; i < DV / 64; ++i) { const int e = lane + 64 * i; float a = 0.f;
;           for (int g = 0; g < NG; ++g) a += OP[(g * 8 + t) * DV + e];
;           for (int s = 0; s <= t; ++s) a += As[t * 8 + s] * Vs[s * DV + e];
.LBB0_1008:
	s_or_b64 exec, exec, s[0:1]
	s_waitcnt lgkmcnt(0)
	v_lshlrev_b32_e32 v0, 12, v68
	s_lshl_b32 s0, s18, 9
	v_add3_u32 v0, 0, v0, v115
	s_add_i32 s8, s0, 0
	ds_write_b128 v0, v[64:67] offset:58624
	ds_write_b128 v0, v[60:63] offset:59136
	ds_write_b128 v0, v[56:59] offset:59648
	ds_write_b128 v0, v[52:55] offset:60160
	ds_write_b128 v0, v[48:51] offset:60672
	ds_write_b128 v0, v[40:43] offset:61184
	ds_write_b128 v0, v[36:39] offset:61696
	ds_write_b128 v0, v[44:47] offset:62208
	v_lshl_add_u32 v1, v114, 2, s8
	s_waitcnt lgkmcnt(0)
	s_waitcnt lgkmcnt(0)
	s_barrier
	ds_read2st64_b32 v[2:3], v1 offset0:229 offset1:245
	v_add_u32_e32 v0, 0xe500, v1
	ds_read2st64_b32 v[4:5], v0 offset0:32 offset1:48
	ds_read2st64_b32 v[6:7], v0 offset0:64 offset1:80
	s_cmp_gt_i32 s18, -1
	s_waitcnt lgkmcnt(0)
	v_add_f32_e32 v2, 0, v2
	v_add_f32_e32 v2, v2, v3
	v_add_f32_e32 v4, v2, v4
	ds_read2st64_b32 v[2:3], v0 offset0:96 offset1:112
	v_add_f32_e32 v4, v4, v5
	v_add_f32_e32 v6, v4, v6
	ds_read2st64_b32 v[4:5], v0 offset0:128 offset1:144
	v_add_f32_e32 v6, v6, v7
	s_waitcnt lgkmcnt(0)
	v_add_f32_e32 v2, v6, v2
	v_add_f32_e32 v6, v2, v3
	ds_read2st64_b32 v[2:3], v0 offset0:160 offset1:176
	v_add_f32_e32 v4, v6, v4
	ds_read2st64_b32 v[6:7], v0 offset0:192 offset1:208
	v_add_f32_e32 v8, v4, v5
	ds_read2st64_b32 v[4:5], v0 offset0:224 offset1:240
	s_waitcnt lgkmcnt(0)
	v_add_f32_e32 v0, v8, v2
	v_add_f32_e32 v0, v0, v3
	v_add_f32_e32 v0, v0, v6
	v_add_f32_e32 v0, v0, v7
	s_cselect_b64 s[0:1], -1, 0
	s_lshl_b32 s8, s18, 5
	v_add_f32_e32 v0, v0, v4
	s_cmp_lt_i32 s18, 0
	v_add_f32_e32 v0, v0, v5
	s_cbranch_scc1 .LBB0_1011
	s_add_i32 s9, s8, 0
	v_readlane_b32 s11, v255, 14
	s_add_i32 s9, s9, 0xa400
	s_add_i32 s10, s18, 1
	v_lshl_add_u32 v2, v114, 2, s11

; #define LAS __attribute__((address_space(3)))
; #define BSYNC() do { asm volatile("s_waitcnt vmcnt(0) lgkmcnt(0)" ::: "memory"); __syncthreads(); } while (0)
; template <int TY> __device__ __forceinline__ void sample_item(const Params& p, ldsp lds, int item) {
;     ...
;     for (int t = 0; t < 8; ++t) *(LAS f32x4*)(OP + (dg * 8 + t) * DV + e4 * 4) = o[t];
;     BSYNC();
;     { const int t = wave; float val[DV / 64]; float ssq = 0.f;
; #pragma unroll
;       for (int i = 0; i < DV / 64; ++i) { const int e = lane + 64 * i; float a = 0.f;
;           for (int g = 0; g < NG; ++g) a += OP[(g * 8 + t) * DV + e];
;           for (int s = 0; s <= t; ++s) a += As[t * 8 + s] * Vs[s * DV + e];
.LBB0_1042:
	s_or_b64 exec, exec, s[0:1]
	s_waitcnt lgkmcnt(0)
	v_lshlrev_b32_e32 v0, 12, v68
	s_lshl_b32 s0, s21, 9
	v_add3_u32 v0, 0, v0, v117
	s_add_i32 s8, s0, 0
	ds_write_b128 v0, v[64:67] offset:58624
	ds_write_b128 v0, v[60:63] offset:59136
	ds_write_b128 v0, v[56:59] offset:59648
	ds_write_b128 v0, v[52:55] offset:60160
	ds_write_b128 v0, v[48:51] offset:60672
	ds_write_b128 v0, v[40:43] offset:61184
	ds_write_b128 v0, v[36:39] offset:61696
	ds_write_b128 v0, v[44:47] offset:62208
	v_lshl_add_u32 v1, v116, 2, s8
	s_waitcnt lgkmcnt(0)
	s_waitcnt lgkmcnt(0)
	s_barrier
	ds_read2st64_b32 v[2:3], v1 offset0:229 offset1:245
	v_add_u32_e32 v0, 0xe500, v1
	ds_read2st64_b32 v[4:5], v0 offset0:32 offset1:48
	ds_read2st64_b32 v[6:7], v0 offset0:64 offset1:80
	s_cmp_gt_i32 s21, -1
	s_waitcnt lgkmcnt(0)
	v_add_f32_e32 v2, 0, v2
	v_add_f32_e32 v2, v2, v3
	v_add_f32_e32 v4, v2, v4
	ds_read2st64_b32 v[2:3], v0 offset0:96 offset1:112
	v_add_f32_e32 v4, v4, v5
	v_add_f32_e32 v6, v4, v6
	ds_read2st64_b32 v[4:5], v0 offset0:128 offset1:144
	v_add_f32_e32 v6, v6, v7
	s_waitcnt lgkmcnt(0)
	v_add_f32_e32 v2, v6, v2
	v_add_f32_e32 v6, v2, v3
	ds_read2st64_b32 v[2:3], v0 offset0:160 offset1:176
	v_add_f32_e32 v4, v6, v4
	ds_read2st64_b32 v[6:7], v0 offset0:192 offset1:208
	v_add_f32_e32 v8, v4, v5
	ds_read2st64_b32 v[4:5], v0 offset0:224 offset1:240
	s_waitcnt lgkmcnt(0)
	v_add_f32_e32 v0, v8, v2
	v_add_f32_e32 v0, v0, v3
	v_add_f32_e32 v0, v0, v6
	v_add_f32_e32 v0, v0, v7
	s_cselect_b64 s[0:1], -1, 0
	s_lshl_b32 s8, s21, 5
	v_add_f32_e32 v0, v0, v4
	s_cmp_lt_i32 s21, 0
	v_add_f32_e32 v0, v0, v5
	s_cbranch_scc1 .LBB0_1045
	s_add_i32 s9, s8, 0
	v_readlane_b32 s11, v255, 14
	s_add_i32 s9, s9, 0xa400
	s_add_i32 s10, s21, 1
	v_lshl_add_u32 v2, v116, 2, s11

; __device__ __forceinline__ unsigned pk2(float lo, float hi) { return pg8::cvt_pk_bf16(lo, hi); }
; __device__ __forceinline__ f32x4 mma16(bf16x8 a, bf16x8 b, f32x4 c) { return __builtin_amdgcn_mfma_f32_16x16x32_bf16(a, b, c, 0, 0, 0); }
; #define BSYNC() do { asm volatile("s_waitcnt vmcnt(0) lgkmcnt(0)" ::: "memory"); __syncthreads(); } while (0)
; template <int TY> __device__ __forceinline__ void ma_even_item(const Params& p, ldsp lds, int item) {
;     ...
;     f32x4 acc[DK / 16];
; #pragma unroll
;     for (int i = 0; i < DK / 16; ++i) acc[i] = (f32x4){0.f, 0.f, 0.f, 0.f};
; #pragma unroll
;     for (int ks = 0; ks < 2; ++ks) { const bf16x8 bf = ldfrag(VT, (16 * wave + l15) * 72 + 32 * ks + 8 * q4);
; #pragma unroll
;         for (int i = 0; i < DK / 16; ++i) acc[i] = mma16(ldfrag(KHT, (16 * i + l15) * 72 + 32 * ks + 8 * q4), bf, acc[i]); }
;     bf16_t* HL = (bf16_t*)(p.ws + WS_HL + (TY ? HL_HGRN : 0)) + ((size_t)item * 128 + 16 * wave + l15) * DK;
; #pragma unroll
;     for (int i = 0; i < DK / 16; ++i) { u32x2 w; w.x = pk2(acc[i][0], acc[i][1]); w.y = pk2(acc[i][2], acc[i][3]); *(u32x2*)(HL + 16 * i + 4 * q4) = w; }
;     BSYNC();
.LBB0_1048:
	s_or_b64 exec, exec, s[0:1]
	v_and_b32_e32 v0, 63, v0
	s_lshl_b32 s0, s8, 4
	v_lshrrev_b32_e32 v0, 1, v0
	v_mov_b32_e32 v12, 0x480
	v_mov_b32_e32 v18, 0x900
	v_mov_b32_e32 v22, 0xd80
	v_or_b32_e32 v1, s0, v7
	v_and_b32_e32 v16, 24, v0
	v_mad_u32_u24 v30, v7, s53, v12
	v_mad_u32_u24 v31, v7, s53, v18
	v_mad_u32_u24 v32, v7, s53, v22
	v_mad_u64_u32 v[0:1], s[8:9], v1, s53, v[16:17]
	v_mad_u32_u24 v8, v7, s53, v16
	v_add_u32_e32 v12, v16, v30
	v_add_u32_e32 v18, v16, v31
	v_add_u32_e32 v22, v16, v32
	v_lshl_add_u32 v6, v0, 1, 0
	v_lshl_add_u32 v8, v8, 1, 0
	v_lshl_add_u32 v12, v12, 1, 0
	v_lshl_add_u32 v18, v18, 1, 0
	v_lshl_add_u32 v22, v22, 1, 0
	s_waitcnt vmcnt(0) lgkmcnt(0)
	s_waitcnt lgkmcnt(0)
	s_barrier
	ds_read_b128 v[0:3], v6 offset:59392
	ds_read_b128 v[8:11], v8 offset:40960
	ds_read_b128 v[12:15], v12 offset:40960
	ds_read_b128 v[18:21], v18 offset:40960
	ds_read_b128 v[22:25], v22 offset:40960
	s_waitcnt lgkmcnt(3)
	v_mfma_f32_16x16x32_bf16 v[8:11], v[8:11], v[0:3], 0
	v_lshlrev_b64 v[4:5], 7, v[4:5]
	s_ashr_i32 s1, s0, 31
	v_lshl_add_u64 v[4:5], v[4:5], 0, s[0:1]
	s_waitcnt lgkmcnt(2)
	v_mfma_f32_16x16x32_bf16 v[12:15], v[12:15], v[0:3], 0
	v_or_b32_e32 v4, v4, v7
	v_readlane_b32 s0, v253, 34
	v_lshlrev_b64 v[4:5], 7, v[4:5]
	s_waitcnt lgkmcnt(1)
	v_mfma_f32_16x16x32_bf16 v[18:21], v[18:21], v[0:3], 0
	v_readlane_b32 s1, v253, 35
	s_waitcnt lgkmcnt(0)
	v_mfma_f32_16x16x32_bf16 v[0:3], v[22:25], v[0:3], 0
	ds_read_b128 v[22:25], v6 offset:59456
	v_or_b32_e32 v6, 32, v16
	v_mad_u32_u24 v26, v7, s53, v6
	v_lshl_add_u32 v26, v26, 1, 0
	ds_read_b128 v[26:29], v26 offset:40960
	v_lshl_add_u64 v[4:5], s[0:1], 0, v[4:5]
	s_waitcnt lgkmcnt(0)
	v_mfma_f32_16x16x32_bf16 v[8:11], v[26:29], v[22:25], v[8:11]
	v_add_u32_e32 v26, v6, v30
	v_lshl_add_u32 v26, v26, 1, 0
	ds_read_b128 v[26:29], v26 offset:40960
	v_lshl_add_u64 v[4:5], v[4:5], 0, v[16:17]
	s_waitcnt lgkmcnt(0)
	v_mfma_f32_16x16x32_bf16 v[12:15], v[26:29], v[22:25], v[12:15]
	v_add_u32_e32 v26, v6, v31
	v_lshl_add_u32 v26, v26, 1, 0
	ds_read_b128 v[26:29], v26 offset:40960
	v_add_u32_e32 v6, v6, v32
	v_lshl_add_u32 v6, v6, 1, 0
	s_waitcnt lgkmcnt(0)
	v_mfma_f32_16x16x32_bf16 v[18:21], v[26:29], v[22:25], v[18:21]
	ds_read_b128 v[26:29], v6 offset:40960
	v_cvt_pk_bf16_f32 v6, v8, v9
	v_cvt_pk_bf16_f32 v7, v10, v11
	s_waitcnt lgkmcnt(0)
	v_mfma_f32_16x16x32_bf16 v[0:3], v[26:29], v[22:25], v[0:3]
	global_store_dwordx2 v[4:5], v[6:7], off
	v_cvt_pk_bf16_f32 v6, v12, v13
	v_cvt_pk_bf16_f32 v7, v14, v15
	global_store_dwordx2 v[4:5], v[6:7], off offset:32
	v_cvt_pk_bf16_f32 v6, v18, v19
	v_cvt_pk_bf16_f32 v7, v20, v21
	global_store_dwordx2 v[4:5], v[6:7], off offset:64
	v_cvt_pk_bf16_f32 v0, v0, v1
	v_cvt_pk_bf16_f32 v1, v2, v3
	s_nop 4
	global_store_dwordx2 v[4:5], v[0:1], off offset:96
	s_waitcnt lgkmcnt(0)
	s_barrier

; __device__ __forceinline__ unsigned pk2(float lo, float hi) { return pg8::cvt_pk_bf16(lo, hi); }
; __device__ __forceinline__ f32x4 mma16(bf16x8 a, bf16x8 b, f32x4 c) { return __builtin_amdgcn_mfma_f32_16x16x32_bf16(a, b, c, 0, 0, 0); }
; #define BSYNC() do { asm volatile("s_waitcnt vmcnt(0) lgkmcnt(0)" ::: "memory"); __syncthreads(); } while (0)
; template <int TY> __device__ __forceinline__ void ma_even_item(const Params& p, ldsp lds, int item) {
;     ...
;     BSYNC();
;     f32x4 acc[DK / 16];
; #pragma unroll
;     for (int i = 0; i < DK / 16; ++i) acc[i] = (f32x4){0.f, 0.f, 0.f, 0.f};
; #pragma unroll
;     for (int ks = 0; ks < 2; ++ks) { const bf16x8 bf = ldfrag(VT, (16 * wave + l15) * 72 + 32 * ks + 8 * q4);
; #pragma unroll
;         for (int i = 0; i < DK / 16; ++i) acc[i] = mma16(ldfrag(KHT, (16 * i + l15) * 72 + 32 * ks + 8 * q4), bf, acc[i]); }
;     bf16_t* HL = (bf16_t*)(p.ws + WS_HL + (TY ? HL_HGRN : 0)) + ((size_t)item * 128 + 16 * wave + l15) * DK;
; #pragma unroll
;     for (int i = 0; i < DK / 16; ++i) { u32x2 w; w.x = pk2(acc[i][0], acc[i][1]); w.y = pk2(acc[i][2], acc[i][3]); *(u32x2*)(HL + 16 * i + 4 * q4) = w; }
;     BSYNC();
.LBB0_1056:
	s_or_b64 exec, exec, s[0:1]
	v_and_b32_e32 v0, 63, v74
	v_lshrrev_b32_e32 v0, 1, v0
	v_and_b32_e32 v44, 15, v74
	v_and_b32_e32 v16, 24, v0
	v_mad_u32_u24 v4, v44, s53, v16
	v_lshl_add_u32 v4, v4, 1, 0
	s_waitcnt lgkmcnt(0)
	s_waitcnt lgkmcnt(0)
	s_barrier
	s_lshl_b32 s0, s8, 4
	ds_read_b128 v[4:7], v4 offset:40960
	v_or_b32_e32 v1, s0, v44
	v_mad_u64_u32 v[0:1], s[8:9], v1, s53, v[16:17]
	v_lshl_add_u32 v40, v0, 1, 0
	ds_read_b128 v[0:3], v40 offset:59392
	v_mov_b32_e32 v36, 0x1f80
	v_mad_u32_u24 v51, v44, s53, v36
	v_add_u32_e32 v36, v16, v51
	v_lshl_add_u32 v36, v36, 1, 0
	ds_read_b128 v[36:39], v36 offset:40960
	s_waitcnt lgkmcnt(1)
	v_mfma_f32_16x16x32_bf16 v[30:33], v[4:7], v[0:3], 0
	v_mov_b32_e32 v4, 0x480
	v_mad_u32_u24 v45, v44, s53, v4
	v_add_u32_e32 v4, v16, v45
	v_lshl_add_u32 v4, v4, 1, 0
	ds_read_b128 v[4:7], v4 offset:40960
	v_or_b32_e32 v52, 32, v16
	s_waitcnt lgkmcnt(0)
	v_mfma_f32_16x16x32_bf16 v[26:29], v[4:7], v[0:3], 0
	v_mov_b32_e32 v4, 0x900
	v_mad_u32_u24 v46, v44, s53, v4
	v_add_u32_e32 v4, v16, v46
	v_lshl_add_u32 v4, v4, 1, 0
	ds_read_b128 v[4:7], v4 offset:40960
	v_lshlrev_b64 v[34:35], 7, v[34:35]
	s_waitcnt lgkmcnt(0)
	v_mfma_f32_16x16x32_bf16 v[22:25], v[4:7], v[0:3], 0
	v_mov_b32_e32 v4, 0xd80
	v_mad_u32_u24 v47, v44, s53, v4
	v_add_u32_e32 v4, v16, v47
	v_lshl_add_u32 v4, v4, 1, 0
	ds_read_b128 v[4:7], v4 offset:40960
	s_ashr_i32 s1, s0, 31
	s_waitcnt lgkmcnt(0)
	v_mfma_f32_16x16x32_bf16 v[18:21], v[4:7], v[0:3], 0
	v_mov_b32_e32 v4, 0x1200
	v_mad_u32_u24 v48, v44, s53, v4
	v_add_u32_e32 v4, v16, v48
	v_lshl_add_u32 v4, v4, 1, 0
	ds_read_b128 v[4:7], v4 offset:40960
	v_lshl_add_u64 v[34:35], v[34:35], 0, s[0:1]
	s_waitcnt lgkmcnt(0)
	v_mfma_f32_16x16x32_bf16 v[12:15], v[4:7], v[0:3], 0
	v_mov_b32_e32 v4, 0x1680
	v_mad_u32_u24 v49, v44, s53, v4
	v_add_u32_e32 v4, v16, v49
	v_lshl_add_u32 v4, v4, 1, 0
	ds_read_b128 v[4:7], v4 offset:40960
	v_or_b32_e32 v34, v34, v44
	s_waitcnt lgkmcnt(0)
	v_mfma_f32_16x16x32_bf16 v[8:11], v[4:7], v[0:3], 0
	v_mov_b32_e32 v4, 0x1b00
	v_mad_u32_u24 v50, v44, s53, v4
	v_add_u32_e32 v4, v16, v50
	v_lshl_add_u32 v4, v4, 1, 0
	ds_read_b128 v[4:7], v4 offset:40960
	v_readlane_b32 s0, v253, 55
	s_waitcnt lgkmcnt(0)
	v_mfma_f32_16x16x32_bf16 v[4:7], v[4:7], v[0:3], 0
	v_lshlrev_b64 v[34:35], 8, v[34:35]
	v_readlane_b32 s1, v253, 56
	v_mfma_f32_16x16x32_bf16 v[0:3], v[36:39], v[0:3], 0
	ds_read_b128 v[36:39], v40 offset:59456
	v_mad_u32_u24 v40, v44, s53, v52
	v_lshl_add_u32 v40, v40, 1, 0
	ds_read_b128 v[40:43], v40 offset:40960
	v_lshl_add_u64 v[34:35], s[0:1], 0, v[34:35]
	s_waitcnt lgkmcnt(0)
	v_mfma_f32_16x16x32_bf16 v[30:33], v[40:43], v[36:39], v[30:33]
	v_add_u32_e32 v40, v52, v45
	v_lshl_add_u32 v40, v40, 1, 0
	ds_read_b128 v[40:43], v40 offset:40960
	v_lshl_add_u64 v[34:35], v[34:35], 0, v[16:17]
	s_waitcnt lgkmcnt(0)
	v_mfma_f32_16x16x32_bf16 v[26:29], v[40:43], v[36:39], v[26:29]
	v_add_u32_e32 v40, v52, v46
	v_lshl_add_u32 v40, v40, 1, 0
	ds_read_b128 v[40:43], v40 offset:40960
	s_waitcnt lgkmcnt(0)
	v_mfma_f32_16x16x32_bf16 v[22:25], v[40:43], v[36:39], v[22:25]
	v_add_u32_e32 v40, v52, v47
	v_lshl_add_u32 v40, v40, 1, 0
	ds_read_b128 v[40:43], v40 offset:40960
	s_waitcnt lgkmcnt(0)
	v_mfma_f32_16x16x32_bf16 v[18:21], v[40:43], v[36:39], v[18:21]
	v_add_u32_e32 v40, v52, v48
	v_lshl_add_u32 v40, v40, 1, 0
	ds_read_b128 v[40:43], v40 offset:40960
	s_waitcnt lgkmcnt(0)
	v_mfma_f32_16x16x32_bf16 v[12:15], v[40:43], v[36:39], v[12:15]
	v_add_u32_e32 v40, v52, v49
	v_lshl_add_u32 v40, v40, 1, 0
	ds_read_b128 v[40:43], v40 offset:40960
	s_waitcnt lgkmcnt(0)
	v_mfma_f32_16x16x32_bf16 v[8:11], v[40:43], v[36:39], v[8:11]
	v_add_u32_e32 v40, v52, v50
	v_lshl_add_u32 v40, v40, 1, 0
	ds_read_b128 v[40:43], v40 offset:40960
	s_waitcnt lgkmcnt(0)
	v_mfma_f32_16x16x32_bf16 v[4:7], v[40:43], v[36:39], v[4:7]
	v_add_u32_e32 v40, v52, v51
	v_lshl_add_u32 v40, v40, 1, 0
	ds_read_b128 v[40:43], v40 offset:40960
	v_cvt_pk_bf16_f32 v30, v30, v31
	v_cvt_pk_bf16_f32 v31, v32, v33
	global_store_dwordx2 v[34:35], v[30:31], off
	s_waitcnt lgkmcnt(0)
	v_mfma_f32_16x16x32_bf16 v[0:3], v[40:43], v[36:39], v[0:3]
	v_cvt_pk_bf16_f32 v26, v26, v27
	v_cvt_pk_bf16_f32 v27, v28, v29
	global_store_dwordx2 v[34:35], v[26:27], off offset:32
	v_cvt_pk_bf16_f32 v22, v22, v23
	v_cvt_pk_bf16_f32 v23, v24, v25
	global_store_dwordx2 v[34:35], v[22:23], off offset:64
	v_cvt_pk_bf16_f32 v18, v18, v19
	v_cvt_pk_bf16_f32 v19, v20, v21
	global_store_dwordx2 v[34:35], v[18:19], off offset:96
	v_cvt_pk_bf16_f32 v12, v12, v13
	v_cvt_pk_bf16_f32 v13, v14, v15
	global_store_dwordx2 v[34:35], v[12:13], off offset:128
	v_cvt_pk_bf16_f32 v8, v8, v9
	v_cvt_pk_bf16_f32 v9, v10, v11
	global_store_dwordx2 v[34:35], v[8:9], off offset:160
	v_cvt_pk_bf16_f32 v4, v4, v5
	v_cvt_pk_bf16_f32 v5, v6, v7
	global_store_dwordx2 v[34:35], v[4:5], off offset:192
	v_cvt_pk_bf16_f32 v0, v0, v1
	v_cvt_pk_bf16_f32 v1, v2, v3
	s_nop 1
	global_store_dwordx2 v[34:35], v[0:1], off offset:224
	s_waitcnt lgkmcnt(0)
	s_barrier
	s_branch .LBB0_1049

; __device__ __forceinline__ float siluf(float x) { return x * __builtin_amdgcn_rcpf(1.0f + __expf(-x)); }
; #define BSYNC() do { asm volatile("s_waitcnt vmcnt(0) lgkmcnt(0)" ::: "memory"); __syncthreads(); } while (0)
; template <int TY> __device__ __forceinline__ void mc_item(const Params& p, ldsp lds, int item) {
;     ...
;     BSYNC();
; #pragma unroll
;     for (int tk = 0; tk < 4; ++tk) { float s = 0.f;
; #pragma unroll
;         for (int w = 0; w < 8; ++w) s += RED[w * 64 + 16 * tk + l15];
;         rstd[tk] = rsqrtf(s * (1.0f / DV) + EPS); }
;     const float* nwp = TY == 0 ? p.in[12] : (TY == 1 ? p.in[14] : p.in[17]);
;     const int goff = TY == 0 ? E_RA + h * 128 : (TY == 1 ? E_GB + h * 128 : O_G + h * 512);
;     constexpr int LDY = TY == 2 ? 2048 : 1024; const int ycol = TY == 0 ? h * 128 : (TY == 1 ? 512 + h * 128 : h * 512);
;     bf16_t* Y = (bf16_t*)(p.ws + WS_Y);
; #pragma unroll
;     for (int ei = 0; ei < ET; ++ei) { const int e0 = 16 * (wave * ET + ei) + 4 * q4; const f32x4 w4 = *(const f32x4*)(nwp + e0);
; #pragma unroll
;         for (int tk = 0; tk < 4; ++tk) { const size_t row = (size_t)row0 + 16 * tk + l15;
;             const u32x2 gw = *(const u32x2*)(Pb + row * PP + goff + e0);
;             const float g0 = bf2f(gw.x & 0xffffu), g1 = bf2f(gw.x >> 16), g2 = bf2f(gw.y & 0xffffu), g3 = bf2f(gw.y >> 16);
;             const f32x4 v = acc[ei][tk] * rstd[tk] * w4;
;             float y0 = v[0] * siluf(g0), y1 = v[1] * siluf(g1), y2 = v[2] * siluf(g2), y3 = v[3] * siluf(g3);
.LBB0_1239:
	s_or_b64 exec, exec, s[0:1]
	s_lshl_b32 s9, s15, 1
	s_add_u32 s0, s26, s9
	v_or_b32_e32 v18, s12, v28
	s_addc_u32 s1, s27, 0
	v_or_b32_e32 v22, s16, v30
	s_waitcnt lgkmcnt(0)
	v_ashrrev_i32_e32 v19, 31, v18
	v_mov_b64_e32 v[28:29], s[0:1]
	v_lshlrev_b64 v[26:27], 1, v[18:19]
	v_mad_i64_i32 v[24:25], s[0:1], v22, s55, v[28:29]
	v_lshl_add_u64 v[24:25], v[24:25], 0, v[26:27]
	s_waitcnt vmcnt(0) lgkmcnt(0)
	s_barrier
	global_load_dwordx2 v[48:49], v[24:25], off offset:2048
	v_readlane_b32 s76, v252, 20
	v_readlane_b32 s84, v252, 28
	v_readlane_b32 s85, v252, 29
	v_lshl_add_u32 v16, v30, 2, 0
	v_add_u32_e32 v32, 0xd800, v16
	v_lshl_add_u64 v[20:21], v[18:19], 2, s[84:85]
	global_load_dwordx4 v[18:21], v[20:21], off
	v_or_b32_e32 v134, 16, v22
	v_mad_i64_i32 v[140:141], s[0:1], v134, s55, v[28:29]
	v_lshl_add_u64 v[142:143], v[140:141], 0, v[26:27]
	global_load_dwordx2 v[144:145], v[142:143], off offset:2048
	v_or_b32_e32 v146, 32, v22
	v_mad_i64_i32 v[148:149], s[0:1], v146, s55, v[28:29]
	v_lshl_add_u64 v[150:151], v[148:149], 0, v[26:27]
	v_or_b32_e32 v152, 48, v22
	global_load_dwordx2 v[154:155], v[150:151], off offset:2048
	v_mad_i64_i32 v[156:157], s[0:1], v152, s55, v[28:29]
	v_lshl_add_u64 v[166:167], v[156:157], 0, v[26:27]
	global_load_dwordx2 v[168:169], v[166:167], off offset:2048
	v_add_u32_e32 v16, 0xdc00, v16
	ds_read2_b32 v[24:25], v32 offset1:16
	ds_read2_b32 v[50:51], v32 offset0:64 offset1:80
	ds_read2_b32 v[52:53], v32 offset0:128 offset1:144
	ds_read2_b32 v[54:55], v32 offset0:192 offset1:208
	ds_read2_b32 v[56:57], v16 offset1:16
	ds_read2_b32 v[58:59], v16 offset0:64 offset1:80
	ds_read2_b32 v[60:61], v16 offset0:128 offset1:144
	ds_read2_b32 v[62:63], v16 offset0:192 offset1:208
	ds_read2_b32 v[46:47], v32 offset0:32 offset1:48
	ds_read2_b32 v[44:45], v32 offset0:96 offset1:112
	ds_read2_b32 v[42:43], v32 offset0:160 offset1:176
	ds_read2_b32 v[40:41], v32 offset0:224 offset1:240
	ds_read2_b32 v[38:39], v16 offset0:32 offset1:48
	ds_read2_b32 v[36:37], v16 offset0:96 offset1:112
	ds_read2_b32 v[34:35], v16 offset0:160 offset1:176
	ds_read2_b32 v[32:33], v16 offset0:224 offset1:240
	s_waitcnt lgkmcnt(14)
	v_mov_b32_e32 v64, v25
	v_mov_b32_e32 v65, v24
	v_mov_b32_e32 v24, v51
	v_mov_b32_e32 v25, v50
	s_waitcnt lgkmcnt(13)
	v_mov_b32_e32 v50, v53
	v_mov_b32_e32 v51, v52
	s_waitcnt lgkmcnt(12)
	v_mov_b32_e32 v52, v55
	v_mov_b32_e32 v53, v54
	s_waitcnt lgkmcnt(11)
	v_mov_b32_e32 v54, v57
	v_mov_b32_e32 v55, v56
	s_waitcnt lgkmcnt(10)
	v_mov_b32_e32 v56, v59
	v_mov_b32_e32 v57, v58
	s_waitcnt lgkmcnt(9)
	v_mov_b32_e32 v58, v61
	v_mov_b32_e32 v59, v60
	s_waitcnt lgkmcnt(8)
	v_mov_b32_e32 v60, v63
	v_mov_b32_e32 v61, v62
	v_pk_add_f32 v[62:63], v[64:65], 0 op_sel_hi:[1,0]
	s_mov_b32 s0, 0x358637bd
	v_pk_add_f32 v[24:25], v[62:63], v[24:25]
	v_mov_b64_e32 v[30:31], s[0:1]
	v_pk_add_f32 v[24:25], v[24:25], v[50:51]
	v_mov_b32_e32 v23, s8
	v_pk_add_f32 v[24:25], v[24:25], v[52:53]
	s_brev_b32 s8, 60
	v_pk_add_f32 v[24:25], v[24:25], v[54:55]
	s_add_u32 s0, s61, s9
	v_pk_add_f32 v[24:25], v[24:25], v[56:57]
	v_readlane_b32 s1, v253, 31
	v_pk_add_f32 v[24:25], v[24:25], v[58:59]
	s_addc_u32 s1, s1, 0
	v_pk_add_f32 v[24:25], v[24:25], v[60:61]
	v_readlane_b32 s77, v252, 21
	v_pk_fma_f32 v[50:51], v[24:25], s[8:9], v[30:31] op_sel_hi:[1,0,0]
	v_lshl_add_u64 v[24:25], s[0:1], 0, v[26:27]
	v_mul_f32_e32 v16, 0x4b800000, v51
	v_cmp_gt_f32_e32 vcc, s33, v51
	v_readlane_b32 s78, v252, 22
	v_readlane_b32 s79, v252, 23
	v_cndmask_b32_e32 v16, v51, v16, vcc
	v_rsq_f32_e32 v16, v16
	v_readlane_b32 s80, v252, 24
	v_readlane_b32 s81, v252, 25
	v_readlane_b32 s82, v252, 26
	v_mul_f32_e32 v51, 0x45800000, v16
	v_cndmask_b32_e32 v16, v16, v51, vcc
	v_pk_mul_f32 v[12:13], v[12:13], v[16:17] op_sel_hi:[1,0]
	v_pk_mul_f32 v[14:15], v[14:15], v[16:17] op_sel_hi:[1,0]
	v_cmp_gt_f32_e32 vcc, s33, v50
	v_readlane_b32 s83, v252, 27
	v_readlane_b32 s86, v252, 30
	v_readlane_b32 s87, v252, 31
	v_readlane_b32 s88, v252, 32
	v_readlane_b32 s89, v252, 33
	v_readlane_b32 s90, v252, 34
	v_readlane_b32 s91, v252, 35
	s_waitcnt vmcnt(0)
; __device__ __forceinline__ unsigned pk2(float lo, float hi) { return pg8::cvt_pk_bf16(lo, hi); }
; __device__ __forceinline__ float siluf(float x) { return x * __builtin_amdgcn_rcpf(1.0f + __expf(-x)); }
; #define BSYNC() do { asm volatile("s_waitcnt vmcnt(0) lgkmcnt(0)" ::: "memory"); __syncthreads(); } while (0)
; template <int TY> __device__ __forceinline__ void mc_item(const Params& p, ldsp lds, int item) {
;     ...
;     for (int ei = 0; ei < ET; ++ei) { const int e0 = 16 * (wave * ET + ei) + 4 * q4; const f32x4 w4 = *(const f32x4*)(nwp + e0);
; #pragma unroll
;         for (int tk = 0; tk < 4; ++tk) { const size_t row = (size_t)row0 + 16 * tk + l15;
;             const u32x2 gw = *(const u32x2*)(Pb + row * PP + goff + e0);
;             const float g0 = bf2f(gw.x & 0xffffu), g1 = bf2f(gw.x >> 16), g2 = bf2f(gw.y & 0xffffu), g3 = bf2f(gw.y >> 16);
;             const f32x4 v = acc[ei][tk] * rstd[tk] * w4;
;             float y0 = v[0] * siluf(g0), y1 = v[1] * siluf(g1), y2 = v[2] * siluf(g2), y3 = v[3] * siluf(g3);
;     ...
;             if (!(fabsf(y0) < 1e30f)) y0 = 0.f; if (!(fabsf(y1) < 1e30f)) y1 = 0.f; if (!(fabsf(y2) < 1e30f)) y2 = 0.f; if (!(fabsf(y3) < 1e30f)) y3 = 0.f;
;     ...
;             u32x2 o; o.x = pk2(y0, y1); o.y = pk2(y2, y3);
;             *(u32x2*)(Y + row * LDY + ycol + e0) = o; } }
;     BSYNC();
	v_lshlrev_b32_e32 v16, 16, v48
	v_mul_f32_e32 v52, 0xbfb8aa3b, v16
	v_exp_f32_e32 v52, v52
	v_and_b32_e32 v48, 0xffff0000, v48
	v_lshlrev_b32_e32 v51, 16, v49
	v_and_b32_e32 v49, 0xffff0000, v49
	v_mul_f32_e32 v53, 0xbfb8aa3b, v48
	v_mul_f32_e32 v54, 0xbfb8aa3b, v51
	v_mul_f32_e32 v55, 0xbfb8aa3b, v49
	v_exp_f32_e32 v53, v53
	v_add_f32_e32 v52, 1.0, v52
	v_exp_f32_e32 v54, v54
	v_exp_f32_e32 v55, v55
	v_rcp_f32_e32 v52, v52
	v_add_f32_e32 v53, 1.0, v53
	v_pk_mul_f32 v[12:13], v[12:13], v[18:19]
	v_add_f32_e32 v54, 1.0, v54
	v_rcp_f32_e32 v53, v53
	v_add_f32_e32 v55, 1.0, v55
	v_mul_f32_e32 v16, v52, v16
	v_rcp_f32_e32 v54, v54
	v_mul_f32_e32 v12, v12, v16
	v_rcp_f32_e32 v16, v55
	v_mul_f32_e32 v48, v53, v48
	v_pk_mul_f32 v[14:15], v[14:15], v[20:21]
	v_mul_f32_e32 v13, v13, v48
	v_mul_f32_e32 v48, v54, v51
	v_mul_f32_e32 v16, v16, v49
	v_mul_f32_e32 v14, v14, v48
	v_mul_f32_e32 v15, v15, v16
	v_cvt_pk_bf16_f32 v12, v12, v13
	v_cvt_pk_bf16_f32 v13, v14, v15
	v_lshlrev_b64 v[14:15], 11, v[22:23]
	v_lshl_add_u64 v[14:15], v[24:25], 0, v[14:15]
	global_store_dwordx2 v[14:15], v[12:13], off
	v_or_b32_e32 v12, 16, v22
	v_mad_i64_i32 v[14:15], s[0:1], v12, s55, v[28:29]
	v_lshl_add_u64 v[14:15], v[14:15], 0, v[26:27]
	v_mul_f32_e32 v16, 0x4b800000, v50
	v_cndmask_b32_e32 v16, v50, v16, vcc
	v_rsq_f32_e32 v16, v16
	v_mov_b32_e32 v13, v23
	v_or_b32_e32 v48, 32, v22
	v_lshlrev_b64 v[12:13], 11, v[12:13]
	v_mul_f32_e32 v49, 0x45800000, v16
	v_cndmask_b32_e32 v16, v16, v49, vcc
	v_pk_mul_f32 v[8:9], v[8:9], v[16:17] op_sel_hi:[1,0]
	v_pk_mul_f32 v[10:11], v[10:11], v[16:17] op_sel_hi:[1,0]
	v_pk_mul_f32 v[8:9], v[8:9], v[18:19]
	v_mad_i64_i32 v[50:51], s[0:1], v48, s55, v[28:29]
	v_lshl_add_u64 v[12:13], v[24:25], 0, v[12:13]
	v_pk_mul_f32 v[10:11], v[10:11], v[20:21]
	v_lshl_add_u64 v[50:51], v[50:51], 0, v[26:27]
	v_or_b32_e32 v22, 48, v22
	v_lshlrev_b32_e32 v16, 16, v144
	v_and_b32_e32 v14, 0xffff0000, v144
	v_lshlrev_b32_e32 v49, 16, v145
	v_and_b32_e32 v15, 0xffff0000, v145
	v_mul_f32_e32 v52, 0xbfb8aa3b, v16
	v_mul_f32_e32 v53, 0xbfb8aa3b, v14
	v_mul_f32_e32 v54, 0xbfb8aa3b, v49
	v_mul_f32_e32 v55, 0xbfb8aa3b, v15
	v_exp_f32_e32 v52, v52
	v_exp_f32_e32 v53, v53
	v_exp_f32_e32 v54, v54
	v_exp_f32_e32 v55, v55
	v_add_f32_e32 v52, 1.0, v52
	v_add_f32_e32 v53, 1.0, v53
	v_add_f32_e32 v54, 1.0, v54
	v_add_f32_e32 v55, 1.0, v55
	v_rcp_f32_e32 v52, v52
	v_rcp_f32_e32 v53, v53
	v_rcp_f32_e32 v54, v54
	v_rcp_f32_e32 v55, v55
	v_mul_f32_e32 v16, v52, v16
	v_mul_f32_e32 v14, v53, v14
	v_mul_f32_e32 v49, v54, v49
	v_mul_f32_e32 v15, v55, v15
	v_mul_f32_e32 v8, v8, v16
	v_mul_f32_e32 v9, v9, v14
	v_mul_f32_e32 v10, v10, v49
	v_mul_f32_e32 v11, v11, v15
	v_cvt_pk_bf16_f32 v8, v8, v9
	v_cvt_pk_bf16_f32 v9, v10, v11
	global_store_dwordx2 v[12:13], v[8:9], off
	s_waitcnt lgkmcnt(7)
	v_mov_b32_e32 v12, v47
	v_mov_b32_e32 v13, v46
	s_waitcnt lgkmcnt(6)
	v_mov_b32_e32 v14, v45
	v_mov_b32_e32 v15, v44
	v_pk_add_f32 v[12:13], v[12:13], 0 op_sel_hi:[1,0]
	s_waitcnt lgkmcnt(5)
	v_mov_b32_e32 v44, v43
	v_mov_b32_e32 v45, v42
	v_pk_add_f32 v[12:13], v[12:13], v[14:15]
	s_waitcnt lgkmcnt(4)
	v_mov_b32_e32 v42, v41
	v_mov_b32_e32 v43, v40
	v_pk_add_f32 v[12:13], v[12:13], v[44:45]
	s_waitcnt lgkmcnt(3)
	v_mov_b32_e32 v40, v39
	v_mov_b32_e32 v41, v38
	v_pk_add_f32 v[12:13], v[12:13], v[42:43]
	s_waitcnt lgkmcnt(2)
	v_mov_b32_e32 v38, v37
	v_mov_b32_e32 v39, v36
	v_pk_add_f32 v[12:13], v[12:13], v[40:41]
	s_waitcnt lgkmcnt(1)
	v_mov_b32_e32 v36, v35
	v_mov_b32_e32 v37, v34
	v_pk_add_f32 v[12:13], v[12:13], v[38:39]
	s_waitcnt lgkmcnt(0)
	v_mov_b32_e32 v34, v33
	v_mov_b32_e32 v35, v32
	v_pk_add_f32 v[12:13], v[12:13], v[36:37]
	v_mov_b32_e32 v49, v23
	v_pk_add_f32 v[12:13], v[12:13], v[34:35]
	v_lshlrev_b64 v[10:11], 11, v[48:49]
	v_pk_fma_f32 v[12:13], v[12:13], s[8:9], v[30:31] op_sel_hi:[1,0,0]
	v_lshl_add_u64 v[10:11], v[24:25], 0, v[10:11]
	v_mul_f32_e32 v14, 0x4b800000, v13
	v_cmp_gt_f32_e32 vcc, s33, v13
	s_nop 1
	v_cndmask_b32_e32 v13, v13, v14, vcc
	v_rsq_f32_e32 v13, v13
	v_mad_i64_i32 v[14:15], s[0:1], v22, s55, v[28:29]
	v_lshl_add_u64 v[14:15], v[14:15], 0, v[26:27]
	v_mul_f32_e32 v16, 0x45800000, v13
	v_cndmask_b32_e32 v16, v13, v16, vcc
	v_pk_mul_f32 v[4:5], v[4:5], v[16:17] op_sel_hi:[1,0]
	v_pk_mul_f32 v[6:7], v[6:7], v[16:17] op_sel_hi:[1,0]
	v_pk_mul_f32 v[4:5], v[18:19], v[4:5]
	v_pk_mul_f32 v[6:7], v[20:21], v[6:7]
	v_cmp_gt_f32_e32 vcc, s33, v12
	v_lshlrev_b32_e32 v13, 16, v154
	v_and_b32_e32 v8, 0xffff0000, v154
	v_lshlrev_b32_e32 v16, 16, v155
	v_and_b32_e32 v9, 0xffff0000, v155
	v_mul_f32_e32 v26, 0xbfb8aa3b, v13
	v_mul_f32_e32 v27, 0xbfb8aa3b, v8
	v_mul_f32_e32 v28, 0xbfb8aa3b, v16
	v_mul_f32_e32 v29, 0xbfb8aa3b, v9
	v_exp_f32_e32 v26, v26
	v_exp_f32_e32 v27, v27
	v_exp_f32_e32 v28, v28
	v_exp_f32_e32 v29, v29
	v_add_f32_e32 v26, 1.0, v26
	v_add_f32_e32 v27, 1.0, v27
	v_add_f32_e32 v28, 1.0, v28
	v_add_f32_e32 v29, 1.0, v29
	v_rcp_f32_e32 v26, v26
	v_rcp_f32_e32 v27, v27
	v_rcp_f32_e32 v28, v28
	v_rcp_f32_e32 v29, v29
	v_mul_f32_e32 v13, v26, v13
	v_mul_f32_e32 v8, v27, v8
	v_mul_f32_e32 v16, v28, v16
	v_mul_f32_e32 v9, v29, v9
	v_mul_f32_e32 v4, v4, v13
	v_mul_f32_e32 v5, v5, v8
	v_mul_f32_e32 v6, v6, v16
	v_mul_f32_e32 v7, v7, v9
	v_cvt_pk_bf16_f32 v4, v4, v5
	v_cvt_pk_bf16_f32 v5, v6, v7
	global_store_dwordx2 v[10:11], v[4:5], off
	v_mul_f32_e32 v6, 0x4b800000, v12
	v_cndmask_b32_e32 v6, v12, v6, vcc
	v_rsq_f32_e32 v8, v6
	v_lshlrev_b64 v[6:7], 11, v[22:23]
	v_mul_f32_e32 v9, 0x45800000, v8
	v_cndmask_b32_e32 v8, v8, v9, vcc
	v_pk_mul_f32 v[0:1], v[0:1], v[8:9] op_sel_hi:[1,0]
	v_pk_mul_f32 v[2:3], v[2:3], v[8:9] op_sel_hi:[1,0]
	v_pk_mul_f32 v[0:1], v[18:19], v[0:1]
	v_pk_mul_f32 v[2:3], v[20:21], v[2:3]
	v_lshlrev_b32_e32 v8, 16, v168
	v_and_b32_e32 v4, 0xffff0000, v168
	v_lshlrev_b32_e32 v9, 16, v169
	v_and_b32_e32 v5, 0xffff0000, v169
	v_mul_f32_e32 v10, 0xbfb8aa3b, v8
	v_mul_f32_e32 v11, 0xbfb8aa3b, v4
	v_mul_f32_e32 v12, 0xbfb8aa3b, v9
	v_mul_f32_e32 v13, 0xbfb8aa3b, v5
	v_exp_f32_e32 v10, v10
	v_exp_f32_e32 v11, v11
	v_exp_f32_e32 v12, v12
	v_exp_f32_e32 v13, v13
	v_add_f32_e32 v10, 1.0, v10
	v_add_f32_e32 v11, 1.0, v11
	v_add_f32_e32 v12, 1.0, v12
	v_add_f32_e32 v13, 1.0, v13
	v_rcp_f32_e32 v10, v10
	v_rcp_f32_e32 v11, v11
	v_rcp_f32_e32 v12, v12
	v_rcp_f32_e32 v13, v13
	v_mul_f32_e32 v8, v10, v8
	v_mul_f32_e32 v4, v11, v4
	v_mul_f32_e32 v9, v12, v9
	v_mul_f32_e32 v5, v13, v5
	v_mul_f32_e32 v0, v0, v8
	v_mul_f32_e32 v1, v1, v4
	v_mul_f32_e32 v2, v2, v9
	v_mul_f32_e32 v3, v3, v5
	v_cvt_pk_bf16_f32 v0, v0, v1
	v_cvt_pk_bf16_f32 v1, v2, v3
	v_lshl_add_u64 v[2:3], v[24:25], 0, v[6:7]
	global_store_dwordx2 v[2:3], v[0:1], off
	s_waitcnt lgkmcnt(0)
	s_barrier

; __device__ __forceinline__ float siluf(float x) { return x * __builtin_amdgcn_rcpf(1.0f + __expf(-x)); }
; #define BSYNC() do { asm volatile("s_waitcnt vmcnt(0) lgkmcnt(0)" ::: "memory"); __syncthreads(); } while (0)
; template <int TY> __device__ __forceinline__ void mc_item(const Params& p, ldsp lds, int item) {
;     ...
;     BSYNC();
; #pragma unroll
;     for (int tk = 0; tk < 4; ++tk) { float s = 0.f;
; #pragma unroll
;         for (int w = 0; w < 8; ++w) s += RED[w * 64 + 16 * tk + l15];
;         rstd[tk] = rsqrtf(s * (1.0f / DV) + EPS); }
;     const float* nwp = TY == 0 ? p.in[12] : (TY == 1 ? p.in[14] : p.in[17]);
;     const int goff = TY == 0 ? E_RA + h * 128 : (TY == 1 ? E_GB + h * 128 : O_G + h * 512);
;     constexpr int LDY = TY == 2 ? 2048 : 1024; const int ycol = TY == 0 ? h * 128 : (TY == 1 ? 512 + h * 128 : h * 512);
;     bf16_t* Y = (bf16_t*)(p.ws + WS_Y);
; #pragma unroll
;     for (int ei = 0; ei < ET; ++ei) { const int e0 = 16 * (wave * ET + ei) + 4 * q4; const f32x4 w4 = *(const f32x4*)(nwp + e0);
; #pragma unroll
;         for (int tk = 0; tk < 4; ++tk) { const size_t row = (size_t)row0 + 16 * tk + l15;
;             const u32x2 gw = *(const u32x2*)(Pb + row * PP + goff + e0);
;             const float g0 = bf2f(gw.x & 0xffffu), g1 = bf2f(gw.x >> 16), g2 = bf2f(gw.y & 0xffffu), g3 = bf2f(gw.y >> 16);
;             const f32x4 v = acc[ei][tk] * rstd[tk] * w4;
;             float y0 = v[0] * siluf(g0), y1 = v[1] * siluf(g1), y2 = v[2] * siluf(g2), y3 = v[3] * siluf(g3);
.LBB0_1254:
	s_or_b64 exec, exec, s[0:1]
	v_lshl_add_u32 v8, v24, 2, 0
	v_add_u32_e32 v16, 0x13800, v8
	v_or_b32_e32 v22, s17, v24
	s_waitcnt vmcnt(0) lgkmcnt(0)
	s_waitcnt lgkmcnt(0)
	s_barrier
	ds_read2_b32 v[8:9], v16 offset1:16
	ds_read2_b32 v[10:11], v16 offset0:64 offset1:80
	ds_read2_b32 v[24:25], v16 offset0:128 offset1:144
	ds_read2_b32 v[26:27], v16 offset0:192 offset1:208
	v_add_u32_e32 v40, 0x400, v16
	s_waitcnt lgkmcnt(3)
	v_mov_b32_e32 v36, v9
	v_mov_b32_e32 v37, v8
	v_pk_add_f32 v[8:9], v[36:37], 0 op_sel_hi:[1,0]
	s_waitcnt lgkmcnt(2)
	v_mov_b32_e32 v36, v11
	v_mov_b32_e32 v37, v10
	ds_read2_b32 v[28:29], v40 offset1:16
	ds_read2_b32 v[30:31], v40 offset0:64 offset1:80
	ds_read2_b32 v[32:33], v40 offset0:128 offset1:144
	ds_read2_b32 v[34:35], v40 offset0:192 offset1:208
	v_pk_add_f32 v[8:9], v[8:9], v[36:37]
	s_waitcnt lgkmcnt(5)
	v_mov_b32_e32 v10, v25
	v_mov_b32_e32 v11, v24
	v_pk_add_f32 v[8:9], v[8:9], v[10:11]
	s_waitcnt lgkmcnt(4)
	v_mov_b32_e32 v10, v27
	v_mov_b32_e32 v11, v26
	v_pk_add_f32 v[8:9], v[8:9], v[10:11]
	s_waitcnt lgkmcnt(3)
	v_mov_b32_e32 v10, v29
	v_mov_b32_e32 v11, v28
	v_pk_add_f32 v[8:9], v[8:9], v[10:11]
	s_waitcnt lgkmcnt(2)
	v_mov_b32_e32 v10, v31
	v_mov_b32_e32 v11, v30
	v_pk_add_f32 v[8:9], v[8:9], v[10:11]
	s_waitcnt lgkmcnt(1)
	v_mov_b32_e32 v10, v33
	v_mov_b32_e32 v11, v32
	v_pk_add_f32 v[8:9], v[8:9], v[10:11]
	s_waitcnt lgkmcnt(0)
	v_mov_b32_e32 v10, v35
	v_mov_b32_e32 v11, v34
	s_mov_b32 s0, 0x358637bd
	v_pk_add_f32 v[8:9], v[8:9], v[10:11]
	v_mov_b64_e32 v[10:11], s[0:1]
	s_brev_b32 s18, 60
	v_pk_fma_f32 v[8:9], v[8:9], s[18:19], v[10:11] op_sel_hi:[1,0,0]
	v_readlane_b32 s76, v252, 20
	v_mul_f32_e32 v24, 0x4b800000, v9
	v_cmp_gt_f32_e64 s[0:1], s33, v9
	v_cmp_gt_f32_e32 vcc, s33, v8
	v_readlane_b32 s88, v252, 32
	v_cndmask_b32_e64 v9, v9, v24, s[0:1]
	v_rsq_f32_e32 v9, v9
	v_readlane_b32 s89, v252, 33
	v_readlane_b32 s77, v252, 21
	v_readlane_b32 s78, v252, 22
	v_mul_f32_e32 v24, 0x45800000, v9
	v_cndmask_b32_e64 v32, v9, v24, s[0:1]
	v_mul_f32_e32 v9, 0x4b800000, v8
	v_cndmask_b32_e32 v8, v8, v9, vcc
	v_rsq_f32_e32 v8, v8
	v_readlane_b32 s79, v252, 23
	v_readlane_b32 s80, v252, 24
	v_readlane_b32 s81, v252, 25
	v_mul_f32_e32 v9, 0x45800000, v8
	v_cndmask_b32_e32 v30, v8, v9, vcc
	ds_read2_b32 v[8:9], v16 offset0:32 offset1:48
	ds_read2_b32 v[24:25], v16 offset0:96 offset1:112
	ds_read2_b32 v[26:27], v16 offset0:160 offset1:176
	ds_read2_b32 v[28:29], v16 offset0:224 offset1:240
	ds_read2_b32 v[34:35], v40 offset0:32 offset1:48
	ds_read2_b32 v[36:37], v40 offset0:96 offset1:112
	ds_read2_b32 v[38:39], v40 offset0:160 offset1:176
	ds_read2_b32 v[40:41], v40 offset0:224 offset1:240
	s_waitcnt lgkmcnt(7)
	v_mov_b32_e32 v42, v9
	v_mov_b32_e32 v43, v8
	v_pk_add_f32 v[8:9], v[42:43], 0 op_sel_hi:[1,0]
	s_waitcnt lgkmcnt(6)
	v_mov_b32_e32 v42, v25
	v_mov_b32_e32 v43, v24
	v_pk_add_f32 v[8:9], v[8:9], v[42:43]
	s_waitcnt lgkmcnt(5)
	v_mov_b32_e32 v24, v27
	v_mov_b32_e32 v25, v26
	v_pk_add_f32 v[8:9], v[8:9], v[24:25]
	s_waitcnt lgkmcnt(4)
	v_mov_b32_e32 v24, v29
	v_mov_b32_e32 v25, v28
	v_pk_add_f32 v[8:9], v[8:9], v[24:25]
	s_waitcnt lgkmcnt(3)
	v_mov_b32_e32 v24, v35
	v_mov_b32_e32 v25, v34
	v_pk_add_f32 v[8:9], v[8:9], v[24:25]
	s_waitcnt lgkmcnt(2)
	v_mov_b32_e32 v24, v37
	v_mov_b32_e32 v25, v36
	v_pk_add_f32 v[8:9], v[8:9], v[24:25]
	s_waitcnt lgkmcnt(1)
	v_mov_b32_e32 v24, v39
	v_mov_b32_e32 v25, v38
	v_pk_add_f32 v[8:9], v[8:9], v[24:25]
	s_waitcnt lgkmcnt(0)
	v_mov_b32_e32 v24, v41
	v_mov_b32_e32 v25, v40
	v_pk_add_f32 v[8:9], v[8:9], v[24:25]
	v_or_b32_e32 v24, s13, v23
	v_pk_fma_f32 v[8:9], v[8:9], s[18:19], v[10:11] op_sel_hi:[1,0,0]
	s_add_u32 s18, s26, s16
	v_mul_f32_e32 v10, 0x4b800000, v9
	v_cmp_gt_f32_e64 s[0:1], s33, v9
	v_cmp_gt_f32_e32 vcc, s33, v8
	s_addc_u32 s19, s27, 0
	v_cndmask_b32_e64 v9, v9, v10, s[0:1]
	v_rsq_f32_e32 v9, v9
	v_ashrrev_i32_e32 v25, 31, v24
	v_mov_b64_e32 v[28:29], s[18:19]
	v_mov_b32_e32 v23, s9
	v_mul_f32_e32 v10, 0x45800000, v9
	v_cndmask_b32_e64 v26, v9, v10, s[0:1]
	v_mul_f32_e32 v9, 0x4b800000, v8
	v_cndmask_b32_e32 v8, v8, v9, vcc
	v_rsq_f32_e32 v8, v8
	s_add_u32 s0, s68, s16
	v_mad_i64_i32 v[34:35], s[16:17], v22, s55, v[28:29]
	v_mul_f32_e32 v9, 0x45800000, v8
	v_cndmask_b32_e32 v16, v8, v9, vcc
	v_lshl_add_u64 v[8:9], v[24:25], 2, s[88:89]
	v_lshlrev_b64 v[24:25], 1, v[24:25]
	v_lshl_add_u64 v[34:35], v[34:35], 0, v[24:25]
	v_add_co_u32_e32 v34, vcc, s57, v34
	global_load_dwordx4 v[8:11], v[8:9], off
	s_nop 0
	v_addc_co_u32_e32 v35, vcc, 0, v35, vcc
	global_load_dwordx2 v[34:35], v[34:35], off offset:2048
	s_mov_b32 s98, s57
	s_mov_b32 s99, 0
	v_or_b32_e32 v64, 16, v22
	v_mad_i64_i32 v[134:135], s[16:17], v64, s55, v[28:29]
	v_lshl_add_u64 v[140:141], v[134:135], 0, v[24:25]
	v_lshl_add_u64 v[142:143], v[140:141], 0, s[98:99]
	global_load_dwordx2 v[144:145], v[142:143], off offset:2048
	v_or_b32_e32 v146, 32, v22
	v_mad_i64_i32 v[148:149], s[16:17], v146, s55, v[28:29]
	v_lshl_add_u64 v[150:151], v[148:149], 0, v[24:25]
	v_lshl_add_u64 v[152:153], v[150:151], 0, s[98:99]
	global_load_dwordx2 v[154:155], v[152:153], off offset:2048
	v_or_b32_e32 v156, 48, v22
	v_mad_i64_i32 v[166:167], s[16:17], v156, s55, v[28:29]
	v_lshl_add_u64 v[168:169], v[166:167], 0, v[24:25]
	v_lshl_add_u64 v[172:173], v[168:169], 0, s[98:99]
	global_load_dwordx2 v[174:175], v[172:173], off offset:2048
	s_addc_u32 s1, s69, 0
	s_mov_b32 s9, 0x1ec21000
	v_pk_mul_f32 v[0:1], v[0:1], v[16:17] op_sel_hi:[1,0]
	v_pk_mul_f32 v[2:3], v[2:3], v[16:17] op_sel_hi:[1,0]
	v_readlane_b32 s82, v252, 26
	v_readlane_b32 s83, v252, 27
	v_readlane_b32 s84, v252, 28
	v_readlane_b32 s85, v252, 29
	v_readlane_b32 s86, v252, 30
	v_readlane_b32 s87, v252, 31
	v_readlane_b32 s90, v252, 34
	v_readlane_b32 s91, v252, 35
	s_waitcnt vmcnt(0)
; __device__ __forceinline__ unsigned pk2(float lo, float hi) { return pg8::cvt_pk_bf16(lo, hi); }
; __device__ __forceinline__ float siluf(float x) { return x * __builtin_amdgcn_rcpf(1.0f + __expf(-x)); }
; #define BSYNC() do { asm volatile("s_waitcnt vmcnt(0) lgkmcnt(0)" ::: "memory"); __syncthreads(); } while (0)
; template <int TY> __device__ __forceinline__ void mc_item(const Params& p, ldsp lds, int item) {
;     ...
;     for (int ei = 0; ei < ET; ++ei) { const int e0 = 16 * (wave * ET + ei) + 4 * q4; const f32x4 w4 = *(const f32x4*)(nwp + e0);
; #pragma unroll
;         for (int tk = 0; tk < 4; ++tk) { const size_t row = (size_t)row0 + 16 * tk + l15;
;             const u32x2 gw = *(const u32x2*)(Pb + row * PP + goff + e0);
;             const float g0 = bf2f(gw.x & 0xffffu), g1 = bf2f(gw.x >> 16), g2 = bf2f(gw.y & 0xffffu), g3 = bf2f(gw.y >> 16);
;             const f32x4 v = acc[ei][tk] * rstd[tk] * w4;
;             float y0 = v[0] * siluf(g0), y1 = v[1] * siluf(g1), y2 = v[2] * siluf(g2), y3 = v[3] * siluf(g3);
;     ...
;             if (!(fabsf(y0) < 1e30f)) y0 = 0.f; if (!(fabsf(y1) < 1e30f)) y1 = 0.f; if (!(fabsf(y2) < 1e30f)) y2 = 0.f; if (!(fabsf(y3) < 1e30f)) y3 = 0.f;
;     ...
;             u32x2 o; o.x = pk2(y0, y1); o.y = pk2(y2, y3);
;             *(u32x2*)(Y + row * LDY + ycol + e0) = o; } }
;     BSYNC();
	v_pk_mul_f32 v[0:1], v[8:9], v[0:1]
	v_pk_mul_f32 v[2:3], v[10:11], v[2:3]
	v_lshlrev_b32_e32 v27, 16, v34
	v_lshlrev_b32_e32 v33, 16, v35
	v_pk_mul_f32 v[18:19], v[18:19], v[32:33] op_sel_hi:[1,0]
	v_pk_mul_f32 v[20:21], v[20:21], v[32:33] op_sel_hi:[1,0]
	v_mul_f32_e32 v32, 0xbfb8aa3b, v27
	v_exp_f32_e32 v32, v32
	v_and_b32_e32 v31, 0xffff0000, v34
	v_pk_mul_f32 v[18:19], v[18:19], v[8:9]
	v_and_b32_e32 v34, 0xffff0000, v35
	v_add_f32_e32 v32, 1.0, v32
	v_rcp_f32_e32 v32, v32
	v_pk_mul_f32 v[20:21], v[20:21], v[10:11]
	v_mul_f32_e32 v27, v32, v27
	v_mul_f32_e32 v18, v18, v27
	v_mul_f32_e32 v27, 0xbfb8aa3b, v31
	v_exp_f32_e32 v27, v27
	s_nop 0
	v_add_f32_e32 v27, 1.0, v27
	v_rcp_f32_e32 v27, v27
	s_nop 0
	v_mul_f32_e32 v27, v27, v31
	v_mul_f32_e32 v19, v19, v27
	v_mul_f32_e32 v27, 0xbfb8aa3b, v33
	v_exp_f32_e32 v27, v27
	v_cvt_pk_bf16_f32 v18, v18, v19
	s_nop 0
	v_add_f32_e32 v27, 1.0, v27
	v_rcp_f32_e32 v27, v27
	s_nop 0
	v_mul_f32_e32 v27, v27, v33
	v_mul_f32_e32 v20, v20, v27
	v_mul_f32_e32 v27, 0xbfb8aa3b, v34
	v_exp_f32_e32 v27, v27
	s_nop 0
	v_add_f32_e32 v27, 1.0, v27
	v_rcp_f32_e32 v27, v27
	s_nop 0
	v_mul_f32_e32 v27, v27, v34
	v_mul_f32_e32 v21, v21, v27
	v_cvt_pk_bf16_f32 v19, v20, v21
	v_lshlrev_b64 v[20:21], 11, v[22:23]
	v_lshl_add_u64 v[20:21], s[0:1], 0, v[20:21]
	v_lshl_add_u64 v[20:21], v[20:21], 0, v[24:25]
	v_add_co_u32_e32 v20, vcc, s9, v20
	s_nop 1
	v_addc_co_u32_e32 v21, vcc, 0, v21, vcc
	global_store_dwordx2 v[20:21], v[18:19], off offset:1024
	v_or_b32_e32 v18, 16, v22
	v_mad_i64_i32 v[20:21], s[16:17], v18, s55, v[28:29]
	v_lshl_add_u64 v[20:21], v[20:21], 0, v[24:25]
	s_nop 0
	v_mov_b32_e32 v19, v23
	s_nop 0
	v_lshl_add_u64 v[20:21], v[20:21], 0, s[98:99]
	v_lshlrev_b32_e32 v27, 16, v144
	v_lshlrev_b32_e32 v31, 16, v145
	v_pk_mul_f32 v[12:13], v[12:13], v[30:31] op_sel_hi:[1,0]
	v_pk_mul_f32 v[14:15], v[14:15], v[30:31] op_sel_hi:[1,0]
	v_mul_f32_e32 v30, 0xbfb8aa3b, v27
	v_exp_f32_e32 v30, v30
	v_and_b32_e32 v20, 0xffff0000, v144
	v_pk_mul_f32 v[12:13], v[12:13], v[8:9]
	v_and_b32_e32 v21, 0xffff0000, v145
	v_add_f32_e32 v30, 1.0, v30
	v_rcp_f32_e32 v30, v30
	v_pk_mul_f32 v[14:15], v[14:15], v[10:11]
	v_mul_f32_e32 v27, v30, v27
	v_mul_f32_e32 v12, v12, v27
	v_mul_f32_e32 v27, 0xbfb8aa3b, v20
	v_exp_f32_e32 v27, v27
	s_nop 0
	v_add_f32_e32 v27, 1.0, v27
	v_rcp_f32_e32 v27, v27
	s_nop 0
	v_mul_f32_e32 v20, v27, v20
	v_mul_f32_e32 v13, v13, v20
	v_mul_f32_e32 v20, 0xbfb8aa3b, v31
	v_exp_f32_e32 v20, v20
	v_cvt_pk_bf16_f32 v12, v12, v13
	v_pk_mul_f32 v[4:5], v[4:5], v[26:27] op_sel_hi:[1,0]
	v_pk_mul_f32 v[6:7], v[6:7], v[26:27] op_sel_hi:[1,0]
	v_add_f32_e32 v20, 1.0, v20
	v_rcp_f32_e32 v20, v20
	v_pk_mul_f32 v[4:5], v[8:9], v[4:5]
	v_pk_mul_f32 v[6:7], v[10:11], v[6:7]
	v_mul_f32_e32 v20, v20, v31
	v_mul_f32_e32 v14, v14, v20
	v_mul_f32_e32 v20, 0xbfb8aa3b, v21
	v_exp_f32_e32 v20, v20
	s_nop 0
	v_add_f32_e32 v20, 1.0, v20
	v_rcp_f32_e32 v20, v20
	s_nop 0
	v_mul_f32_e32 v20, v20, v21
	v_mul_f32_e32 v15, v15, v20
	v_cvt_pk_bf16_f32 v13, v14, v15
	v_lshlrev_b64 v[14:15], 11, v[18:19]
	v_lshl_add_u64 v[14:15], s[0:1], 0, v[14:15]
	v_lshl_add_u64 v[14:15], v[14:15], 0, v[24:25]
	v_add_co_u32_e32 v14, vcc, s9, v14
	s_nop 1
	v_addc_co_u32_e32 v15, vcc, 0, v15, vcc
	global_store_dwordx2 v[14:15], v[12:13], off offset:1024
	v_or_b32_e32 v12, 32, v22
	v_mad_i64_i32 v[14:15], s[16:17], v12, s55, v[28:29]
	v_lshl_add_u64 v[14:15], v[14:15], 0, v[24:25]
	s_nop 0
	v_mov_b32_e32 v13, v23
	s_nop 0
	v_lshl_add_u64 v[14:15], v[14:15], 0, s[98:99]
	v_or_b32_e32 v22, 48, v22
	v_lshlrev_b32_e32 v18, 16, v154
	v_mul_f32_e32 v20, 0xbfb8aa3b, v18
	v_exp_f32_e32 v20, v20
	v_and_b32_e32 v14, 0xffff0000, v154
	v_lshlrev_b32_e32 v19, 16, v155
	v_and_b32_e32 v15, 0xffff0000, v155
	v_add_f32_e32 v20, 1.0, v20
	v_rcp_f32_e32 v20, v20
	s_nop 0
	v_mul_f32_e32 v18, v20, v18
	v_mul_f32_e32 v4, v4, v18
	v_mul_f32_e32 v18, 0xbfb8aa3b, v14
	v_exp_f32_e32 v18, v18
	s_nop 0
	v_add_f32_e32 v18, 1.0, v18
	v_rcp_f32_e32 v18, v18
	s_nop 0
	v_mul_f32_e32 v14, v18, v14
	v_mul_f32_e32 v5, v5, v14
	v_mul_f32_e32 v14, 0xbfb8aa3b, v19
	v_exp_f32_e32 v14, v14
	v_cvt_pk_bf16_f32 v4, v4, v5
	s_nop 0
	v_add_f32_e32 v14, 1.0, v14
	v_rcp_f32_e32 v14, v14
	s_nop 0
	v_mul_f32_e32 v14, v14, v19
	v_mul_f32_e32 v6, v6, v14
	v_mul_f32_e32 v14, 0xbfb8aa3b, v15
	v_exp_f32_e32 v14, v14
	s_nop 0
	v_add_f32_e32 v14, 1.0, v14
	v_rcp_f32_e32 v14, v14
	s_nop 0
	v_mul_f32_e32 v14, v14, v15
	v_mul_f32_e32 v7, v7, v14
	v_cvt_pk_bf16_f32 v5, v6, v7
	v_lshlrev_b64 v[6:7], 11, v[12:13]
	v_lshl_add_u64 v[6:7], s[0:1], 0, v[6:7]
	v_lshl_add_u64 v[6:7], v[6:7], 0, v[24:25]
	v_add_co_u32_e32 v6, vcc, s9, v6
	s_nop 1
	v_addc_co_u32_e32 v7, vcc, 0, v7, vcc
	global_store_dwordx2 v[6:7], v[4:5], off offset:1024
	v_mad_i64_i32 v[4:5], s[16:17], v22, s55, v[28:29]
	v_lshl_add_u64 v[4:5], v[4:5], 0, v[24:25]
	s_nop 0
	s_nop 1
	v_lshl_add_u64 v[4:5], v[4:5], 0, s[98:99]
	v_lshlrev_b32_e32 v6, 16, v174
	v_mul_f32_e32 v8, 0xbfb8aa3b, v6
	v_exp_f32_e32 v8, v8
	v_and_b32_e32 v4, 0xffff0000, v174
	v_lshlrev_b32_e32 v7, 16, v175
	v_and_b32_e32 v5, 0xffff0000, v175
	v_add_f32_e32 v8, 1.0, v8
	v_rcp_f32_e32 v8, v8
	s_nop 0
	v_mul_f32_e32 v6, v8, v6
	v_mul_f32_e32 v0, v0, v6
	v_mul_f32_e32 v6, 0xbfb8aa3b, v4
	v_exp_f32_e32 v6, v6
	s_nop 0
	v_add_f32_e32 v6, 1.0, v6
	v_rcp_f32_e32 v6, v6
	s_nop 0
	v_mul_f32_e32 v4, v6, v4
	v_mul_f32_e32 v1, v1, v4
	v_mul_f32_e32 v4, 0xbfb8aa3b, v7
	v_exp_f32_e32 v4, v4
	v_cvt_pk_bf16_f32 v0, v0, v1
	s_nop 0
	v_add_f32_e32 v4, 1.0, v4
	v_rcp_f32_e32 v4, v4
	s_nop 0
	v_mul_f32_e32 v4, v4, v7
	v_mul_f32_e32 v2, v2, v4
	v_mul_f32_e32 v4, 0xbfb8aa3b, v5
	v_exp_f32_e32 v4, v4
	s_nop 0
	v_add_f32_e32 v4, 1.0, v4
	v_rcp_f32_e32 v4, v4
	s_nop 0
	v_mul_f32_e32 v4, v4, v5
	v_mul_f32_e32 v3, v3, v4
	v_cvt_pk_bf16_f32 v1, v2, v3
	v_lshlrev_b64 v[2:3], 11, v[22:23]
	v_lshl_add_u64 v[2:3], s[0:1], 0, v[2:3]
	v_lshl_add_u64 v[2:3], v[2:3], 0, v[24:25]
	v_add_co_u32_e32 v2, vcc, 0x1ec21000, v2
	s_nop 1
	v_addc_co_u32_e32 v3, vcc, 0, v3, vcc
	global_store_dwordx2 v[2:3], v[0:1], off offset:1024
	s_waitcnt lgkmcnt(0)
	s_barrier
	s_branch .LBB0_1240
